# all sixteen GEMM K-loop heads placed at 0 mod 8 bytes (.p2align 3)
# baseline (speedup 1.0000x reference)
.LBB0_396:
	s_ashr_i32 s31, s30, 31
	s_lshl_b64 s[34:35], s[30:31], 20
	s_add_u32 s34, s8, s34
	s_addc_u32 s35, s9, s35
	s_and_b64 s[36:37], s[6:7], exec
	s_cselect_b32 s31, s35, s43
	s_cselect_b32 s58, s34, s42
	s_ashr_i32 s29, s28, 31
	s_lshl_b64 s[36:37], s[28:29], 20
	s_add_u32 s36, s12, s36
	s_addc_u32 s37, s13, s37
	s_and_b64 s[44:45], s[6:7], exec
	s_cselect_b32 s29, s37, s41
	s_cselect_b32 s59, s36, s40
	s_add_u32 s60, s40, 0x100
	s_addc_u32 s61, s41, 0
	s_add_u32 s40, s42, 0x80080
	v_mov_b32_e32 v2, 0
	s_addc_u32 s41, s43, 0
	s_mov_b32 s62, -2
	v_mov_b32_e32 v3, v2
	v_mov_b32_e32 v4, v2
	v_mov_b32_e32 v5, v2
	v_mov_b32_e32 v6, v2
	v_mov_b32_e32 v7, v2
	v_mov_b32_e32 v8, v2
	v_mov_b32_e32 v9, v2
	v_mov_b32_e32 v18, v2
	v_mov_b32_e32 v19, v2
	v_mov_b32_e32 v20, v2
	v_mov_b32_e32 v21, v2
	v_mov_b32_e32 v22, v2
	v_mov_b32_e32 v23, v2
	v_mov_b32_e32 v24, v2
	v_mov_b32_e32 v25, v2
	v_mov_b32_e32 v34, v2
	v_mov_b32_e32 v35, v2
	v_mov_b32_e32 v36, v2
	v_mov_b32_e32 v37, v2
	v_mov_b32_e32 v38, v2
	v_mov_b32_e32 v39, v2
	v_mov_b32_e32 v40, v2
	v_mov_b32_e32 v41, v2
	v_mov_b32_e32 v50, v2
	v_mov_b32_e32 v51, v2
	v_mov_b32_e32 v52, v2
	v_mov_b32_e32 v53, v2
	v_mov_b32_e32 v54, v2
	v_mov_b32_e32 v55, v2
	v_mov_b32_e32 v56, v2
	v_mov_b32_e32 v57, v2
	v_mov_b32_e32 v10, v2
	v_mov_b32_e32 v11, v2
	v_mov_b32_e32 v12, v2
	v_mov_b32_e32 v13, v2
	v_mov_b32_e32 v14, v2
	v_mov_b32_e32 v15, v2
	v_mov_b32_e32 v16, v2
	v_mov_b32_e32 v17, v2
	v_mov_b32_e32 v26, v2
	v_mov_b32_e32 v27, v2
	v_mov_b32_e32 v28, v2
	v_mov_b32_e32 v29, v2
	v_mov_b32_e32 v30, v2
	v_mov_b32_e32 v31, v2
	v_mov_b32_e32 v32, v2
	v_mov_b32_e32 v33, v2
	v_mov_b32_e32 v42, v2
	v_mov_b32_e32 v43, v2
	v_mov_b32_e32 v44, v2
	v_mov_b32_e32 v45, v2
	v_mov_b32_e32 v46, v2
	v_mov_b32_e32 v47, v2
	v_mov_b32_e32 v48, v2
	v_mov_b32_e32 v49, v2
	v_mov_b32_e32 v58, v2
	v_mov_b32_e32 v59, v2
	v_mov_b32_e32 v60, v2
	v_mov_b32_e32 v61, v2
	v_mov_b32_e32 v62, v2
	v_mov_b32_e32 v63, v2
	v_mov_b32_e32 v64, v2
	v_mov_b32_e32 v65, v2
	v_mov_b32_e32 v66, v2
	v_mov_b32_e32 v67, v2
	v_mov_b32_e32 v68, v2
	v_mov_b32_e32 v69, v2
	v_mov_b32_e32 v70, v2
	v_mov_b32_e32 v71, v2
	v_mov_b32_e32 v72, v2
	v_mov_b32_e32 v73, v2
	v_mov_b32_e32 v82, v2
	v_mov_b32_e32 v83, v2
	v_mov_b32_e32 v84, v2
	v_mov_b32_e32 v85, v2
	v_mov_b32_e32 v86, v2
	v_mov_b32_e32 v87, v2
	v_mov_b32_e32 v88, v2
	v_mov_b32_e32 v89, v2
	v_mov_b32_e32 v98, v2
	v_mov_b32_e32 v99, v2
	v_mov_b32_e32 v100, v2
	v_mov_b32_e32 v101, v2
	v_mov_b32_e32 v102, v2
	v_mov_b32_e32 v103, v2
	v_mov_b32_e32 v104, v2
	v_mov_b32_e32 v105, v2
	v_mov_b32_e32 v114, v2
	v_mov_b32_e32 v115, v2
	v_mov_b32_e32 v116, v2
	v_mov_b32_e32 v117, v2
	v_mov_b32_e32 v118, v2
	v_mov_b32_e32 v119, v2
	v_mov_b32_e32 v120, v2
	v_mov_b32_e32 v121, v2
	v_mov_b32_e32 v74, v2
	v_mov_b32_e32 v75, v2
	v_mov_b32_e32 v76, v2
	v_mov_b32_e32 v77, v2
	v_mov_b32_e32 v78, v2
	v_mov_b32_e32 v79, v2
	v_mov_b32_e32 v80, v2
	v_mov_b32_e32 v81, v2
	v_mov_b32_e32 v90, v2
	v_mov_b32_e32 v91, v2
	v_mov_b32_e32 v92, v2
	v_mov_b32_e32 v93, v2
	v_mov_b32_e32 v94, v2
	v_mov_b32_e32 v95, v2
	v_mov_b32_e32 v96, v2
	v_mov_b32_e32 v97, v2
	v_mov_b32_e32 v106, v2
	v_mov_b32_e32 v107, v2
	v_mov_b32_e32 v108, v2
	v_mov_b32_e32 v109, v2
	v_mov_b32_e32 v110, v2
	v_mov_b32_e32 v111, v2
	v_mov_b32_e32 v112, v2
	v_mov_b32_e32 v113, v2
	v_mov_b32_e32 v122, v2
	v_mov_b32_e32 v123, v2
	v_mov_b32_e32 v124, v2
	v_mov_b32_e32 v125, v2
	v_mov_b32_e32 v126, v2
	v_mov_b32_e32 v127, v2
	v_mov_b32_e32 v128, v2
	v_mov_b32_e32 v129, v2
	.p2align 3

.LBB0_476:
	s_ashr_i32 s37, s36, 31
	s_lshl_b64 s[38:39], s[36:37], 20
	s_add_u32 s38, s20, s38
	s_addc_u32 s39, s21, s39
	s_and_b64 s[40:41], s[10:11], exec
	s_cselect_b32 s37, s39, s59
	s_cselect_b32 s43, s38, s58
	s_ashr_i32 s35, s34, 31
	s_lshl_b64 s[40:41], s[34:35], 20
	s_add_u32 s40, s22, s40
	s_addc_u32 s41, s23, s41
	s_and_b64 s[60:61], s[10:11], exec
	s_cselect_b32 s35, s41, s47
	s_cselect_b32 s62, s40, s46
	s_add_u32 s63, s46, 0x100
	s_addc_u32 s64, s47, 0
	s_add_u32 s46, s58, 0x80080
	v_mov_b32_e32 v2, 0
	s_addc_u32 s47, s59, 0
	s_mov_b32 s65, -2
	s_waitcnt lgkmcnt(0)
	v_mov_b32_e32 v3, v2
	v_mov_b32_e32 v4, v2
	v_mov_b32_e32 v5, v2
	v_mov_b32_e32 v6, v2
	v_mov_b32_e32 v7, v2
	v_mov_b32_e32 v8, v2
	v_mov_b32_e32 v9, v2
	v_mov_b32_e32 v18, v2
	v_mov_b32_e32 v19, v2
	v_mov_b32_e32 v20, v2
	v_mov_b32_e32 v21, v2
	v_mov_b32_e32 v22, v2
	v_mov_b32_e32 v23, v2
	v_mov_b32_e32 v24, v2
	v_mov_b32_e32 v25, v2
	v_mov_b32_e32 v34, v2
	v_mov_b32_e32 v35, v2
	v_mov_b32_e32 v36, v2
	v_mov_b32_e32 v37, v2
	v_mov_b32_e32 v38, v2
	v_mov_b32_e32 v39, v2
	v_mov_b32_e32 v40, v2
	v_mov_b32_e32 v41, v2
	v_mov_b32_e32 v50, v2
	v_mov_b32_e32 v51, v2
	v_mov_b32_e32 v52, v2
	v_mov_b32_e32 v53, v2
	v_mov_b32_e32 v54, v2
	v_mov_b32_e32 v55, v2
	v_mov_b32_e32 v56, v2
	v_mov_b32_e32 v57, v2
	v_mov_b32_e32 v10, v2
	v_mov_b32_e32 v11, v2
	v_mov_b32_e32 v12, v2
	v_mov_b32_e32 v13, v2
	v_mov_b32_e32 v14, v2
	v_mov_b32_e32 v15, v2
	v_mov_b32_e32 v16, v2
	v_mov_b32_e32 v17, v2
	v_mov_b32_e32 v26, v2
	v_mov_b32_e32 v27, v2
	v_mov_b32_e32 v28, v2
	v_mov_b32_e32 v29, v2
	v_mov_b32_e32 v30, v2
	v_mov_b32_e32 v31, v2
	v_mov_b32_e32 v32, v2
	v_mov_b32_e32 v33, v2
	v_mov_b32_e32 v42, v2
	v_mov_b32_e32 v43, v2
	v_mov_b32_e32 v44, v2
	v_mov_b32_e32 v45, v2
	v_mov_b32_e32 v46, v2
	v_mov_b32_e32 v47, v2
	v_mov_b32_e32 v48, v2
	v_mov_b32_e32 v49, v2
	v_mov_b32_e32 v58, v2
	v_mov_b32_e32 v59, v2
	v_mov_b32_e32 v60, v2
	v_mov_b32_e32 v61, v2
	v_mov_b32_e32 v62, v2
	v_mov_b32_e32 v63, v2
	v_mov_b32_e32 v64, v2
	v_mov_b32_e32 v65, v2
	v_mov_b32_e32 v66, v2
	v_mov_b32_e32 v67, v2
	v_mov_b32_e32 v68, v2
	v_mov_b32_e32 v69, v2
	v_mov_b32_e32 v70, v2
	v_mov_b32_e32 v71, v2
	v_mov_b32_e32 v72, v2
	v_mov_b32_e32 v73, v2
	v_mov_b32_e32 v82, v2
	v_mov_b32_e32 v83, v2
	v_mov_b32_e32 v84, v2
	v_mov_b32_e32 v85, v2
	v_mov_b32_e32 v86, v2
	v_mov_b32_e32 v87, v2
	v_mov_b32_e32 v88, v2
	v_mov_b32_e32 v89, v2
	v_mov_b32_e32 v98, v2
	v_mov_b32_e32 v99, v2
	v_mov_b32_e32 v100, v2
	v_mov_b32_e32 v101, v2
	v_mov_b32_e32 v102, v2
	v_mov_b32_e32 v103, v2
	v_mov_b32_e32 v104, v2
	v_mov_b32_e32 v105, v2
	v_mov_b32_e32 v114, v2
	v_mov_b32_e32 v115, v2
	v_mov_b32_e32 v116, v2
	v_mov_b32_e32 v117, v2
	v_mov_b32_e32 v118, v2
	v_mov_b32_e32 v119, v2
	v_mov_b32_e32 v120, v2
	v_mov_b32_e32 v121, v2
	v_mov_b32_e32 v74, v2
	v_mov_b32_e32 v75, v2
	v_mov_b32_e32 v76, v2
	v_mov_b32_e32 v77, v2
	v_mov_b32_e32 v78, v2
	v_mov_b32_e32 v79, v2
	v_mov_b32_e32 v80, v2
	v_mov_b32_e32 v81, v2
	v_mov_b32_e32 v90, v2
	v_mov_b32_e32 v91, v2
	v_mov_b32_e32 v92, v2
	v_mov_b32_e32 v93, v2
	v_mov_b32_e32 v94, v2
	v_mov_b32_e32 v95, v2
	v_mov_b32_e32 v96, v2
	v_mov_b32_e32 v97, v2
	v_mov_b32_e32 v106, v2
	v_mov_b32_e32 v107, v2
	v_mov_b32_e32 v108, v2
	v_mov_b32_e32 v109, v2
	v_mov_b32_e32 v110, v2
	v_mov_b32_e32 v111, v2
	v_mov_b32_e32 v112, v2
	v_mov_b32_e32 v113, v2
	v_mov_b32_e32 v122, v2
	v_mov_b32_e32 v123, v2
	v_mov_b32_e32 v124, v2
	v_mov_b32_e32 v125, v2
	v_mov_b32_e32 v126, v2
	v_mov_b32_e32 v127, v2
	v_mov_b32_e32 v128, v2
	v_mov_b32_e32 v129, v2
	.p2align 3

.LBB0_558:
	s_lshl_b32 s0, s0, 5
	v_lshlrev_b32_e32 v13, 6, v0
	s_mov_b64 s[20:21], 0x80
	v_lshlrev_b32_e32 v11, 1, v161
	v_lshlrev_b32_e32 v12, 2, v0
	s_and_b32 s29, s0, 0x60
	v_and_b32_e32 v205, 0x3c0, v13
	s_add_i32 m0, s15, 0x18000
	v_lshl_add_u64 v[8:9], v[8:9], 0, s[20:21]
	v_lshl_or_b32 v134, s1, 6, v1
	s_lshl_b32 s1, s1, 13
	v_and_b32_e32 v204, 32, v12
	v_or_b32_e32 v13, v11, v205
	s_lshl_b32 s0, s29, 7
	s_waitcnt vmcnt(2)
	s_barrier
	global_load_lds_dwordx4 v[8:9], off
	v_lshl_add_u64 v[6:7], v[6:7], 0, s[20:21]
	s_add_i32 m0, s15, 0x1a000
	s_add_i32 s45, s15, 0x8000
	s_add_i32 s46, s15, 0xa000
	v_lshl_or_b32 v165, v1, 6, v11
	v_bitop3_b32 v169, v11, v204, v205 bitop3:0x36
	v_bitop3_b32 v11, s0, v13, v204 bitop3:0xf6
	global_load_lds_dwordx4 v[6:7], off
	v_lshl_add_u64 v[4:5], v[4:5], 0, s[20:21]
	s_mov_b32 m0, s45
	s_add_u32 s0, s12, 0x80080
	v_bitop3_b32 v12, v165, s1, v204 bitop3:0xde
	global_load_lds_dwordx4 v[4:5], off
	v_lshl_add_u64 v[2:3], v[2:3], 0, s[20:21]
	s_mov_b32 m0, s46
	s_addc_u32 s1, s13, 0
	global_load_lds_dwordx4 v[2:3], off
	s_add_i32 m0, s15, 0x1c000
	v_lshl_add_u64 v[2:3], s[0:1], 0, v[150:151]
	global_load_lds_dwordx4 v[2:3], off
	v_lshl_add_u64 v[2:3], s[0:1], 0, v[146:147]
	s_add_i32 m0, s15, 0x1e000
	s_add_u32 s0, s22, s34
	global_load_lds_dwordx4 v[2:3], off
	s_addc_u32 s1, s23, s35
	s_add_u32 s47, s0, 0x1200100
	v_lshrrev_b32_e32 v206, 11, v10
	s_addc_u32 s56, s1, 0
	v_lshlrev_b32_e32 v2, 16, v206
	v_lshlrev_b32_e32 v4, 12, v203
	v_or3_b32 v2, v185, v2, v4
	s_add_u32 s30, s22, s30
	v_add_u32_e32 v154, v2, v202
	v_mov_b32_e32 v155, v151
	s_addc_u32 s31, s23, s31
	v_lshl_add_u64 v[2:3], s[30:31], 0, v[154:155]
	s_mov_b64 s[0:1], 0x10a80080
	v_lshrrev_b32_e32 v207, 7, v0
	v_lshl_add_u64 v[130:131], v[2:3], 0, s[0:1]
	v_lshlrev_b32_e32 v2, 16, v207
	v_or3_b32 v2, v185, v2, v4
	v_add_u32_e32 v156, v2, v202
	v_mov_b32_e32 v157, v151
	v_lshl_add_u64 v[2:3], s[30:31], 0, v[156:157]
	s_waitcnt vmcnt(6)
	v_lshl_add_u64 v[132:133], v[2:3], 0, s[0:1]
	s_add_i32 s0, 0, 0x10000
	s_add_i32 s1, 0, 0x14000
	s_add_i32 s33, 0, 0x18000
	s_add_i32 s48, 0, 0x1c000
	s_add_i32 s60, s0, s36
	s_add_i32 s62, s1, s36
	s_add_i32 s64, s33, s36
	s_add_i32 s66, s48, s36
	s_mov_b32 s57, -2
	s_mov_b64 s[34:35], 0
	v_add_u32_e32 v135, s0, v11
	v_add_u32_e32 v136, s1, v11
	v_add_u32_e32 v137, 0, v12
	s_add_i32 s58, s15, 0xc000
	s_add_i32 s59, s15, 0xe000
	s_add_i32 s61, s60, 0x2000
	s_add_i32 s63, s62, 0x2000
	v_add_u32_e32 v138, s33, v11
	v_add_u32_e32 v139, s48, v11
	s_add_i32 s65, s64, 0x2000
	s_add_i32 s67, s66, 0x2000
	v_mov_b32_e32 v2, v151
	v_mov_b32_e32 v3, v151
	v_mov_b32_e32 v4, v151
	v_mov_b32_e32 v5, v151
	v_mov_b32_e32 v6, v151
	v_mov_b32_e32 v7, v151
	v_mov_b32_e32 v8, v151
	v_mov_b32_e32 v9, v151
	v_mov_b32_e32 v10, v151
	v_mov_b32_e32 v11, v151
	v_mov_b32_e32 v12, v151
	v_mov_b32_e32 v13, v151
	v_mov_b32_e32 v14, v151
	v_mov_b32_e32 v15, v151
	v_mov_b32_e32 v16, v151
	v_mov_b32_e32 v17, v151
	v_mov_b32_e32 v18, v151
	v_mov_b32_e32 v19, v151
	v_mov_b32_e32 v20, v151
	v_mov_b32_e32 v21, v151
	v_mov_b32_e32 v22, v151
	v_mov_b32_e32 v23, v151
	v_mov_b32_e32 v24, v151
	v_mov_b32_e32 v25, v151
	v_mov_b32_e32 v26, v151
	v_mov_b32_e32 v27, v151
	v_mov_b32_e32 v28, v151
	v_mov_b32_e32 v29, v151
	v_mov_b32_e32 v30, v151
	v_mov_b32_e32 v31, v151
	v_mov_b32_e32 v32, v151
	v_mov_b32_e32 v33, v151
	v_mov_b32_e32 v62, v151
	v_mov_b32_e32 v63, v151
	v_mov_b32_e32 v64, v151
	v_mov_b32_e32 v65, v151
	v_mov_b32_e32 v66, v151
	v_mov_b32_e32 v67, v151
	v_mov_b32_e32 v68, v151
	v_mov_b32_e32 v69, v151
	v_mov_b32_e32 v74, v151
	v_mov_b32_e32 v75, v151
	v_mov_b32_e32 v76, v151
	v_mov_b32_e32 v77, v151
	v_mov_b32_e32 v78, v151
	v_mov_b32_e32 v79, v151
	v_mov_b32_e32 v80, v151
	v_mov_b32_e32 v81, v151
	v_mov_b32_e32 v82, v151
	v_mov_b32_e32 v83, v151
	v_mov_b32_e32 v84, v151
	v_mov_b32_e32 v85, v151
	v_mov_b32_e32 v86, v151
	v_mov_b32_e32 v87, v151
	v_mov_b32_e32 v88, v151
	v_mov_b32_e32 v89, v151
	v_mov_b32_e32 v90, v151
	v_mov_b32_e32 v91, v151
	v_mov_b32_e32 v92, v151
	v_mov_b32_e32 v93, v151
	v_mov_b32_e32 v94, v151
	v_mov_b32_e32 v95, v151
	v_mov_b32_e32 v96, v151
	v_mov_b32_e32 v97, v151
	v_mov_b32_e32 v34, v151
	v_mov_b32_e32 v35, v151
	v_mov_b32_e32 v36, v151
	v_mov_b32_e32 v37, v151
	v_mov_b32_e32 v38, v151
	v_mov_b32_e32 v39, v151
	v_mov_b32_e32 v40, v151
	v_mov_b32_e32 v41, v151
	v_mov_b32_e32 v42, v151
	v_mov_b32_e32 v43, v151
	v_mov_b32_e32 v44, v151
	v_mov_b32_e32 v45, v151
	v_mov_b32_e32 v46, v151
	v_mov_b32_e32 v47, v151
	v_mov_b32_e32 v48, v151
	v_mov_b32_e32 v49, v151
	v_mov_b32_e32 v50, v151
	v_mov_b32_e32 v51, v151
	v_mov_b32_e32 v52, v151
	v_mov_b32_e32 v53, v151
	v_mov_b32_e32 v54, v151
	v_mov_b32_e32 v55, v151
	v_mov_b32_e32 v56, v151
	v_mov_b32_e32 v57, v151
	v_mov_b32_e32 v58, v151
	v_mov_b32_e32 v59, v151
	v_mov_b32_e32 v60, v151
	v_mov_b32_e32 v61, v151
	v_mov_b32_e32 v70, v151
	v_mov_b32_e32 v71, v151
	v_mov_b32_e32 v72, v151
	v_mov_b32_e32 v73, v151
	v_mov_b32_e32 v98, v151
	v_mov_b32_e32 v99, v151
	v_mov_b32_e32 v100, v151
	v_mov_b32_e32 v101, v151
	v_mov_b32_e32 v102, v151
	v_mov_b32_e32 v103, v151
	v_mov_b32_e32 v104, v151
	v_mov_b32_e32 v105, v151
	v_mov_b32_e32 v106, v151
	v_mov_b32_e32 v107, v151
	v_mov_b32_e32 v108, v151
	v_mov_b32_e32 v109, v151
	v_mov_b32_e32 v110, v151
	v_mov_b32_e32 v111, v151
	v_mov_b32_e32 v112, v151
	v_mov_b32_e32 v113, v151
	v_mov_b32_e32 v114, v151
	v_mov_b32_e32 v115, v151
	v_mov_b32_e32 v116, v151
	v_mov_b32_e32 v117, v151
	v_mov_b32_e32 v118, v151
	v_mov_b32_e32 v119, v151
	v_mov_b32_e32 v120, v151
	v_mov_b32_e32 v121, v151
	v_mov_b32_e32 v122, v151
	v_mov_b32_e32 v123, v151
	v_mov_b32_e32 v124, v151
	v_mov_b32_e32 v125, v151
	v_mov_b32_e32 v126, v151
	v_mov_b32_e32 v127, v151
	v_mov_b32_e32 v128, v151
	v_mov_b32_e32 v129, v151
	s_barrier
	.p2align 3

.LBB0_589:
	s_ashr_i32 s37, s36, 31
	s_lshl_b64 s[40:41], s[36:37], 20
	s_add_u32 s40, s16, s40
	s_addc_u32 s41, s17, s41
	s_and_b64 s[42:43], s[62:63], exec
	s_cselect_b32 s37, s41, s61
	s_cselect_b32 s71, s40, s60
	s_ashr_i32 s39, s38, 31
	s_lshl_b64 s[42:43], s[38:39], 20
	s_add_u32 s42, s52, s42
	s_addc_u32 s43, s53, s43
	s_and_b64 s[62:63], s[62:63], exec
	s_cselect_b32 s39, s43, s59
	s_cselect_b32 s72, s42, s58
	s_add_u32 s73, s58, 0x100
	s_addc_u32 s74, s59, 0
	s_add_u32 s58, s60, 0x80080
	v_mov_b32_e32 v2, 0
	s_addc_u32 s59, s61, 0
	s_mov_b32 s75, -2
	v_mov_b32_e32 v3, v2
	v_mov_b32_e32 v4, v2
	v_mov_b32_e32 v5, v2
	v_mov_b32_e32 v6, v2
	v_mov_b32_e32 v7, v2
	v_mov_b32_e32 v8, v2
	v_mov_b32_e32 v9, v2
	v_mov_b32_e32 v10, v2
	v_mov_b32_e32 v11, v2
	v_mov_b32_e32 v12, v2
	v_mov_b32_e32 v13, v2
	v_mov_b32_e32 v14, v2
	v_mov_b32_e32 v15, v2
	v_mov_b32_e32 v16, v2
	v_mov_b32_e32 v17, v2
	v_mov_b32_e32 v18, v2
	v_mov_b32_e32 v19, v2
	v_mov_b32_e32 v20, v2
	v_mov_b32_e32 v21, v2
	v_mov_b32_e32 v22, v2
	v_mov_b32_e32 v23, v2
	v_mov_b32_e32 v24, v2
	v_mov_b32_e32 v25, v2
	v_mov_b32_e32 v26, v2
	v_mov_b32_e32 v27, v2
	v_mov_b32_e32 v28, v2
	v_mov_b32_e32 v29, v2
	v_mov_b32_e32 v30, v2
	v_mov_b32_e32 v31, v2
	v_mov_b32_e32 v32, v2
	v_mov_b32_e32 v33, v2
	v_mov_b32_e32 v62, v2
	v_mov_b32_e32 v63, v2
	v_mov_b32_e32 v64, v2
	v_mov_b32_e32 v65, v2
	v_mov_b32_e32 v66, v2
	v_mov_b32_e32 v67, v2
	v_mov_b32_e32 v68, v2
	v_mov_b32_e32 v69, v2
	v_mov_b32_e32 v74, v2
	v_mov_b32_e32 v75, v2
	v_mov_b32_e32 v76, v2
	v_mov_b32_e32 v77, v2
	v_mov_b32_e32 v78, v2
	v_mov_b32_e32 v79, v2
	v_mov_b32_e32 v80, v2
	v_mov_b32_e32 v81, v2
	v_mov_b32_e32 v82, v2
	v_mov_b32_e32 v83, v2
	v_mov_b32_e32 v84, v2
	v_mov_b32_e32 v85, v2
	v_mov_b32_e32 v86, v2
	v_mov_b32_e32 v87, v2
	v_mov_b32_e32 v88, v2
	v_mov_b32_e32 v89, v2
	v_mov_b32_e32 v90, v2
	v_mov_b32_e32 v91, v2
	v_mov_b32_e32 v92, v2
	v_mov_b32_e32 v93, v2
	v_mov_b32_e32 v94, v2
	v_mov_b32_e32 v95, v2
	v_mov_b32_e32 v96, v2
	v_mov_b32_e32 v97, v2
	v_mov_b32_e32 v34, v2
	v_mov_b32_e32 v35, v2
	v_mov_b32_e32 v36, v2
	v_mov_b32_e32 v37, v2
	v_mov_b32_e32 v38, v2
	v_mov_b32_e32 v39, v2
	v_mov_b32_e32 v40, v2
	v_mov_b32_e32 v41, v2
	v_mov_b32_e32 v42, v2
	v_mov_b32_e32 v43, v2
	v_mov_b32_e32 v44, v2
	v_mov_b32_e32 v45, v2
	v_mov_b32_e32 v46, v2
	v_mov_b32_e32 v47, v2
	v_mov_b32_e32 v48, v2
	v_mov_b32_e32 v49, v2
	v_mov_b32_e32 v50, v2
	v_mov_b32_e32 v51, v2
	v_mov_b32_e32 v52, v2
	v_mov_b32_e32 v53, v2
	v_mov_b32_e32 v54, v2
	v_mov_b32_e32 v55, v2
	v_mov_b32_e32 v56, v2
	v_mov_b32_e32 v57, v2
	v_mov_b32_e32 v58, v2
	v_mov_b32_e32 v59, v2
	v_mov_b32_e32 v60, v2
	v_mov_b32_e32 v61, v2
	v_mov_b32_e32 v70, v2
	v_mov_b32_e32 v71, v2
	v_mov_b32_e32 v72, v2
	v_mov_b32_e32 v73, v2
	v_mov_b32_e32 v98, v2
	v_mov_b32_e32 v99, v2
	v_mov_b32_e32 v100, v2
	v_mov_b32_e32 v101, v2
	v_mov_b32_e32 v102, v2
	v_mov_b32_e32 v103, v2
	v_mov_b32_e32 v104, v2
	v_mov_b32_e32 v105, v2
	v_mov_b32_e32 v106, v2
	v_mov_b32_e32 v107, v2
	v_mov_b32_e32 v108, v2
	v_mov_b32_e32 v109, v2
	v_mov_b32_e32 v110, v2
	v_mov_b32_e32 v111, v2
	v_mov_b32_e32 v112, v2
	v_mov_b32_e32 v113, v2
	v_mov_b32_e32 v114, v2
	v_mov_b32_e32 v115, v2
	v_mov_b32_e32 v116, v2
	v_mov_b32_e32 v117, v2
	v_mov_b32_e32 v118, v2
	v_mov_b32_e32 v119, v2
	v_mov_b32_e32 v120, v2
	v_mov_b32_e32 v121, v2
	v_mov_b32_e32 v122, v2
	v_mov_b32_e32 v123, v2
	v_mov_b32_e32 v124, v2
	v_mov_b32_e32 v125, v2
	v_mov_b32_e32 v126, v2
	v_mov_b32_e32 v127, v2
	v_mov_b32_e32 v128, v2
	v_mov_b32_e32 v129, v2
	.p2align 3

.LBB0_632:
	s_ashr_i32 s37, s36, 31
	s_lshl_b64 s[40:41], s[36:37], 22
	s_add_u32 s40, s18, s40
	s_addc_u32 s41, s19, s41
	s_and_b64 s[42:43], s[62:63], exec
	s_cselect_b32 s37, s41, s61
	s_cselect_b32 s45, s40, s60
	s_ashr_i32 s39, s38, 31
	s_lshl_b64 s[42:43], s[38:39], 22
	s_add_u32 s42, s49, s42
	s_addc_u32 s43, s51, s43
	s_and_b64 s[62:63], s[62:63], exec
	s_cselect_b32 s39, s43, s59
	s_cselect_b32 s70, s42, s58
	s_add_u32 s71, s58, 0x100
	s_addc_u32 s72, s59, 0
	s_add_u32 s58, s60, 0x200080
	v_mov_b32_e32 v2, 0
	s_addc_u32 s59, s61, 0
	s_mov_b32 s73, -2
	s_waitcnt lgkmcnt(0)
	v_mov_b32_e32 v3, v2
	v_mov_b32_e32 v4, v2
	v_mov_b32_e32 v5, v2
	v_mov_b32_e32 v6, v2
	v_mov_b32_e32 v7, v2
	v_mov_b32_e32 v8, v2
	v_mov_b32_e32 v9, v2
	v_mov_b32_e32 v18, v2
	v_mov_b32_e32 v19, v2
	v_mov_b32_e32 v20, v2
	v_mov_b32_e32 v21, v2
	v_mov_b32_e32 v22, v2
	v_mov_b32_e32 v23, v2
	v_mov_b32_e32 v24, v2
	v_mov_b32_e32 v25, v2
	v_mov_b32_e32 v34, v2
	v_mov_b32_e32 v35, v2
	v_mov_b32_e32 v36, v2
	v_mov_b32_e32 v37, v2
	v_mov_b32_e32 v38, v2
	v_mov_b32_e32 v39, v2
	v_mov_b32_e32 v40, v2
	v_mov_b32_e32 v41, v2
	v_mov_b32_e32 v50, v2
	v_mov_b32_e32 v51, v2
	v_mov_b32_e32 v52, v2
	v_mov_b32_e32 v53, v2
	v_mov_b32_e32 v54, v2
	v_mov_b32_e32 v55, v2
	v_mov_b32_e32 v56, v2
	v_mov_b32_e32 v57, v2
	v_mov_b32_e32 v10, v2
	v_mov_b32_e32 v11, v2
	v_mov_b32_e32 v12, v2
	v_mov_b32_e32 v13, v2
	v_mov_b32_e32 v14, v2
	v_mov_b32_e32 v15, v2
	v_mov_b32_e32 v16, v2
	v_mov_b32_e32 v17, v2
	v_mov_b32_e32 v26, v2
	v_mov_b32_e32 v27, v2
	v_mov_b32_e32 v28, v2
	v_mov_b32_e32 v29, v2
	v_mov_b32_e32 v30, v2
	v_mov_b32_e32 v31, v2
	v_mov_b32_e32 v32, v2
	v_mov_b32_e32 v33, v2
	v_mov_b32_e32 v42, v2
	v_mov_b32_e32 v43, v2
	v_mov_b32_e32 v44, v2
	v_mov_b32_e32 v45, v2
	v_mov_b32_e32 v46, v2
	v_mov_b32_e32 v47, v2
	v_mov_b32_e32 v48, v2
	v_mov_b32_e32 v49, v2
	v_mov_b32_e32 v58, v2
	v_mov_b32_e32 v59, v2
	v_mov_b32_e32 v60, v2
	v_mov_b32_e32 v61, v2
	v_mov_b32_e32 v62, v2
	v_mov_b32_e32 v63, v2
	v_mov_b32_e32 v64, v2
	v_mov_b32_e32 v65, v2
	v_mov_b32_e32 v66, v2
	v_mov_b32_e32 v67, v2
	v_mov_b32_e32 v68, v2
	v_mov_b32_e32 v69, v2
	v_mov_b32_e32 v70, v2
	v_mov_b32_e32 v71, v2
	v_mov_b32_e32 v72, v2
	v_mov_b32_e32 v73, v2
	v_mov_b32_e32 v82, v2
	v_mov_b32_e32 v83, v2
	v_mov_b32_e32 v84, v2
	v_mov_b32_e32 v85, v2
	v_mov_b32_e32 v86, v2
	v_mov_b32_e32 v87, v2
	v_mov_b32_e32 v88, v2
	v_mov_b32_e32 v89, v2
	v_mov_b32_e32 v98, v2
	v_mov_b32_e32 v99, v2
	v_mov_b32_e32 v100, v2
	v_mov_b32_e32 v101, v2
	v_mov_b32_e32 v102, v2
	v_mov_b32_e32 v103, v2
	v_mov_b32_e32 v104, v2
	v_mov_b32_e32 v105, v2
	v_mov_b32_e32 v114, v2
	v_mov_b32_e32 v115, v2
	v_mov_b32_e32 v116, v2
	v_mov_b32_e32 v117, v2
	v_mov_b32_e32 v118, v2
	v_mov_b32_e32 v119, v2
	v_mov_b32_e32 v120, v2
	v_mov_b32_e32 v121, v2
	v_mov_b32_e32 v74, v2
	v_mov_b32_e32 v75, v2
	v_mov_b32_e32 v76, v2
	v_mov_b32_e32 v77, v2
	v_mov_b32_e32 v78, v2
	v_mov_b32_e32 v79, v2
	v_mov_b32_e32 v80, v2
	v_mov_b32_e32 v81, v2
	v_mov_b32_e32 v90, v2
	v_mov_b32_e32 v91, v2
	v_mov_b32_e32 v92, v2
	v_mov_b32_e32 v93, v2
	v_mov_b32_e32 v94, v2
	v_mov_b32_e32 v95, v2
	v_mov_b32_e32 v96, v2
	v_mov_b32_e32 v97, v2
	v_mov_b32_e32 v106, v2
	v_mov_b32_e32 v107, v2
	v_mov_b32_e32 v108, v2
	v_mov_b32_e32 v109, v2
	v_mov_b32_e32 v110, v2
	v_mov_b32_e32 v111, v2
	v_mov_b32_e32 v112, v2
	v_mov_b32_e32 v113, v2
	v_mov_b32_e32 v122, v2
	v_mov_b32_e32 v123, v2
	v_mov_b32_e32 v124, v2
	v_mov_b32_e32 v125, v2
	v_mov_b32_e32 v126, v2
	v_mov_b32_e32 v127, v2
	v_mov_b32_e32 v128, v2
	v_mov_b32_e32 v129, v2
	.p2align 3

.LBB0_715:
	v_bfe_u32 v170, v0, 4, 2
	v_lshlrev_b32_e32 v14, 4, v170
	v_lshlrev_b32_e32 v15, 2, v0
	v_lshl_or_b32 v146, s3, 6, v1
	v_lshl_or_b32 v166, v1, 6, v14
	s_lshl_b32 s3, s3, 13
	v_and_b32_e32 v15, 32, v15
	v_bitop3_b32 v16, v166, s3, v15 bitop3:0xde
	s_lshl_b32 s3, s26, 5
	s_mov_b64 s[26:27], 0x80
	s_and_b32 s23, s3, 0x60
	s_add_i32 m0, s1, 0x18000
	v_lshl_add_u64 v[8:9], v[8:9], 0, s[26:27]
	s_and_b32 s73, s2, 7
	s_lshl_b32 s3, s23, 7
	s_waitcnt vmcnt(2)
	s_barrier
	global_load_lds_dwordx4 v[8:9], off
	v_lshl_add_u64 v[6:7], v[6:7], 0, s[26:27]
	s_add_i32 m0, s1, 0x1a000
	s_add_i32 s39, s1, 0x8000
	s_add_i32 s40, s1, 0xa000
	global_load_lds_dwordx4 v[6:7], off
	v_lshl_add_u64 v[4:5], v[4:5], 0, s[26:27]
	s_mov_b32 m0, s39
	s_add_u32 s36, s14, 0x80080
	global_load_lds_dwordx4 v[4:5], off
	v_lshl_add_u64 v[2:3], v[2:3], 0, s[26:27]
	s_mov_b32 m0, s40
	s_addc_u32 s37, s15, 0
	global_load_lds_dwordx4 v[2:3], off
	s_add_i32 m0, s1, 0x1c000
	v_lshl_add_u64 v[2:3], s[36:37], 0, v[140:141]
	global_load_lds_dwordx4 v[2:3], off
	v_lshl_add_u64 v[2:3], s[36:37], 0, v[142:143]
	s_add_i32 m0, s1, 0x1e000
	v_lshlrev_b32_e32 v17, 6, v0
	global_load_lds_dwordx4 v[2:3], off
	v_and_b32_e32 v17, 0x3c0, v17
	v_or_b32_e32 v18, v14, v17
	v_bitop3_b32 v167, v14, v15, v17 bitop3:0x36
	v_bitop3_b32 v14, s3, v18, v15 bitop3:0xf6
	s_add_u32 s3, s6, s30
	s_addc_u32 s30, s7, s31
	s_add_u32 s41, s3, 0x5300100
	v_lshlrev_b32_e32 v2, 5, v13
	s_addc_u32 s44, s30, 0
	v_and_b32_e32 v2, 0x70000, v2
	v_lshlrev_b32_e32 v4, 12, v12
	v_or3_b32 v2, v10, v2, v4
	s_add_u32 s28, s6, s28
	v_add_u32_e32 v134, v2, v11
	v_mov_b32_e32 v135, v141
	s_addc_u32 s29, s7, s29
	v_lshl_add_u64 v[2:3], s[28:29], 0, v[134:135]
	s_mov_b64 s[30:31], 0x1e280080
	v_lshl_add_u64 v[138:139], v[2:3], 0, s[30:31]
	v_lshlrev_b32_e32 v2, 9, v0
	v_and_b32_e32 v2, 0x30000, v2
	v_or3_b32 v2, v10, v2, v4
	s_waitcnt vmcnt(6)
	v_add_u32_e32 v136, v2, v11
	v_mov_b32_e32 v137, v141
	s_add_i32 s3, 0, 0x10000
	s_add_i32 s45, 0, 0x14000
	s_add_i32 s47, 0, 0x18000
	s_add_i32 s72, 0, 0x1c000
	v_lshl_add_u64 v[2:3], s[28:29], 0, v[136:137]
	s_add_i32 s51, s3, s34
	s_add_i32 s53, s45, s34
	s_add_i32 s57, s47, s34
	s_add_i32 s59, s72, s34
	v_lshl_add_u64 v[144:145], v[2:3], 0, s[30:31]
	s_mov_b32 s46, -2
	s_mov_b64 s[30:31], 0
	v_add_u32_e32 v147, s3, v14
	v_add_u32_e32 v148, s45, v14
	v_add_u32_e32 v149, 0, v16
	s_add_i32 s48, s1, 0xc000
	s_add_i32 s49, s1, 0xe000
	s_add_i32 s52, s51, 0x2000
	s_add_i32 s56, s53, 0x2000
	v_add_u32_e32 v150, s47, v14
	v_add_u32_e32 v151, s72, v14
	s_add_i32 s58, s57, 0x2000
	s_add_i32 s60, s59, 0x2000
	v_mov_b32_e32 v2, v141
	v_mov_b32_e32 v3, v141
	v_mov_b32_e32 v4, v141
	v_mov_b32_e32 v5, v141
	v_mov_b32_e32 v6, v141
	v_mov_b32_e32 v7, v141
	v_mov_b32_e32 v8, v141
	v_mov_b32_e32 v9, v141
	v_mov_b32_e32 v18, v141
	v_mov_b32_e32 v19, v141
	v_mov_b32_e32 v20, v141
	v_mov_b32_e32 v21, v141
	v_mov_b32_e32 v22, v141
	v_mov_b32_e32 v23, v141
	v_mov_b32_e32 v24, v141
	v_mov_b32_e32 v25, v141
	v_mov_b32_e32 v34, v141
	v_mov_b32_e32 v35, v141
	v_mov_b32_e32 v36, v141
	v_mov_b32_e32 v37, v141
	v_mov_b32_e32 v38, v141
	v_mov_b32_e32 v39, v141
	v_mov_b32_e32 v40, v141
	v_mov_b32_e32 v41, v141
	v_mov_b32_e32 v50, v141
	v_mov_b32_e32 v51, v141
	v_mov_b32_e32 v52, v141
	v_mov_b32_e32 v53, v141
	v_mov_b32_e32 v54, v141
	v_mov_b32_e32 v55, v141
	v_mov_b32_e32 v56, v141
	v_mov_b32_e32 v57, v141
	v_mov_b32_e32 v10, v141
	v_mov_b32_e32 v11, v141
	v_mov_b32_e32 v12, v141
	v_mov_b32_e32 v13, v141
	v_mov_b32_e32 v14, v141
	v_mov_b32_e32 v15, v141
	v_mov_b32_e32 v16, v141
	v_mov_b32_e32 v17, v141
	v_mov_b32_e32 v26, v141
	v_mov_b32_e32 v27, v141
	v_mov_b32_e32 v28, v141
	v_mov_b32_e32 v29, v141
	v_mov_b32_e32 v30, v141
	v_mov_b32_e32 v31, v141
	v_mov_b32_e32 v32, v141
	v_mov_b32_e32 v33, v141
	v_mov_b32_e32 v42, v141
	v_mov_b32_e32 v43, v141
	v_mov_b32_e32 v44, v141
	v_mov_b32_e32 v45, v141
	v_mov_b32_e32 v46, v141
	v_mov_b32_e32 v47, v141
	v_mov_b32_e32 v48, v141
	v_mov_b32_e32 v49, v141
	v_mov_b32_e32 v58, v141
	v_mov_b32_e32 v59, v141
	v_mov_b32_e32 v60, v141
	v_mov_b32_e32 v61, v141
	v_mov_b32_e32 v62, v141
	v_mov_b32_e32 v63, v141
	v_mov_b32_e32 v64, v141
	v_mov_b32_e32 v65, v141
	v_mov_b32_e32 v66, v141
	v_mov_b32_e32 v67, v141
	v_mov_b32_e32 v68, v141
	v_mov_b32_e32 v69, v141
	v_mov_b32_e32 v70, v141
	v_mov_b32_e32 v71, v141
	v_mov_b32_e32 v72, v141
	v_mov_b32_e32 v73, v141
	v_mov_b32_e32 v82, v141
	v_mov_b32_e32 v83, v141
	v_mov_b32_e32 v84, v141
	v_mov_b32_e32 v85, v141
	v_mov_b32_e32 v86, v141
	v_mov_b32_e32 v87, v141
	v_mov_b32_e32 v88, v141
	v_mov_b32_e32 v89, v141
	v_mov_b32_e32 v98, v141
	v_mov_b32_e32 v99, v141
	v_mov_b32_e32 v100, v141
	v_mov_b32_e32 v101, v141
	v_mov_b32_e32 v102, v141
	v_mov_b32_e32 v103, v141
	v_mov_b32_e32 v104, v141
	v_mov_b32_e32 v105, v141
	v_mov_b32_e32 v114, v141
	v_mov_b32_e32 v115, v141
	v_mov_b32_e32 v116, v141
	v_mov_b32_e32 v117, v141
	v_mov_b32_e32 v118, v141
	v_mov_b32_e32 v119, v141
	v_mov_b32_e32 v120, v141
	v_mov_b32_e32 v121, v141
	v_mov_b32_e32 v74, v141
	v_mov_b32_e32 v75, v141
	v_mov_b32_e32 v76, v141
	v_mov_b32_e32 v77, v141
	v_mov_b32_e32 v78, v141
	v_mov_b32_e32 v79, v141
	v_mov_b32_e32 v80, v141
	v_mov_b32_e32 v81, v141
	v_mov_b32_e32 v90, v141
	v_mov_b32_e32 v91, v141
	v_mov_b32_e32 v92, v141
	v_mov_b32_e32 v93, v141
	v_mov_b32_e32 v94, v141
	v_mov_b32_e32 v95, v141
	v_mov_b32_e32 v96, v141
	v_mov_b32_e32 v97, v141
	v_mov_b32_e32 v106, v141
	v_mov_b32_e32 v107, v141
	v_mov_b32_e32 v108, v141
	v_mov_b32_e32 v109, v141
	v_mov_b32_e32 v110, v141
	v_mov_b32_e32 v111, v141
	v_mov_b32_e32 v112, v141
	v_mov_b32_e32 v113, v141
	v_mov_b32_e32 v122, v141
	v_mov_b32_e32 v123, v141
	v_mov_b32_e32 v124, v141
	v_mov_b32_e32 v125, v141
	v_mov_b32_e32 v126, v141
	v_mov_b32_e32 v127, v141
	v_mov_b32_e32 v128, v141
	v_mov_b32_e32 v129, v141
	s_barrier
	.p2align 3

.LBB0_744:
	v_lshlrev_b32_e32 v10, 2, v1
	s_lshl_b32 s23, s31, 13
	v_and_b32_e32 v10, 32, v10
	v_lshl_or_b32 v139, s31, 6, v1
	v_bitop3_b32 v10, v166, s23, v10 bitop3:0xde
	s_lshl_b32 s23, s30, 5
	s_mov_b64 s[30:31], 0x80
	s_add_i32 m0, s1, 0x18000
	v_lshl_add_u64 v[2:3], v[2:3], 0, s[30:31]
	s_and_b32 s23, s23, 0x60
	s_waitcnt vmcnt(2)
	s_barrier
	global_load_lds_dwordx4 v[2:3], off
	v_lshl_add_u64 v[2:3], v[4:5], 0, s[30:31]
	s_add_i32 m0, s1, 0x1a000
	s_add_i32 s46, s1, 0x8000
	s_add_i32 s48, s1, 0xa000
	global_load_lds_dwordx4 v[2:3], off
	v_lshl_add_u64 v[2:3], v[8:9], 0, s[30:31]
	s_mov_b32 m0, s46
	s_add_u32 s40, s20, 0x80080
	global_load_lds_dwordx4 v[2:3], off
	v_lshl_add_u64 v[2:3], v[6:7], 0, s[30:31]
	s_mov_b32 m0, s48
	s_addc_u32 s41, s21, 0
	global_load_lds_dwordx4 v[2:3], off
	s_add_i32 m0, s1, 0x1c000
	v_lshl_add_u64 v[2:3], s[40:41], 0, v[140:141]
	global_load_lds_dwordx4 v[2:3], off
	v_lshl_add_u64 v[2:3], s[40:41], 0, v[142:143]
	s_add_i32 m0, s1, 0x1e000
	s_add_u32 s36, s24, s36
	global_load_lds_dwordx4 v[2:3], off
	s_addc_u32 s37, s25, s37
	s_add_u32 s49, s36, 0x5300100
	s_addc_u32 s51, s37, 0
	s_add_u32 s34, s24, s34
	s_addc_u32 s35, s25, s35
	v_lshl_add_u64 v[2:3], s[34:35], 0, v[134:135]
	s_mov_b64 s[36:37], 0x1e280080
	s_waitcnt vmcnt(6)
	v_lshl_add_u64 v[144:145], v[2:3], 0, s[36:37]
	v_lshl_add_u64 v[2:3], s[34:35], 0, v[136:137]
	v_lshl_or_b32 v11, s23, 7, v167
	v_lshl_add_u64 v[146:147], v[2:3], 0, s[36:37]
	v_mov_b32_e32 v2, 0
	s_add_i32 s57, s3, s38
	s_add_i32 s59, s45, s38
	s_add_i32 s61, s47, s38
	s_add_i32 s63, s72, s38
	s_mov_b32 s52, -2
	s_mov_b64 s[36:37], 0
	v_add_u32_e32 v148, s3, v11
	v_add_u32_e32 v149, s45, v11
	v_add_u32_e32 v150, 0, v10
	s_add_i32 s53, s1, 0xc000
	s_add_i32 s56, s1, 0xe000
	s_add_i32 s58, s57, 0x2000
	s_add_i32 s60, s59, 0x2000
	v_add_u32_e32 v151, s47, v11
	v_add_u32_e32 v152, s72, v11
	s_add_i32 s62, s61, 0x2000
	s_add_i32 s64, s63, 0x2000
	v_mov_b32_e32 v3, v2
	v_mov_b32_e32 v4, v2
	v_mov_b32_e32 v5, v2
	v_mov_b32_e32 v6, v2
	v_mov_b32_e32 v7, v2
	v_mov_b32_e32 v8, v2
	v_mov_b32_e32 v9, v2
	v_mov_b32_e32 v18, v2
	v_mov_b32_e32 v19, v2
	v_mov_b32_e32 v20, v2
	v_mov_b32_e32 v21, v2
	v_mov_b32_e32 v22, v2
	v_mov_b32_e32 v23, v2
	v_mov_b32_e32 v24, v2
	v_mov_b32_e32 v25, v2
	v_mov_b32_e32 v34, v2
	v_mov_b32_e32 v35, v2
	v_mov_b32_e32 v36, v2
	v_mov_b32_e32 v37, v2
	v_mov_b32_e32 v38, v2
	v_mov_b32_e32 v39, v2
	v_mov_b32_e32 v40, v2
	v_mov_b32_e32 v41, v2
	v_mov_b32_e32 v50, v2
	v_mov_b32_e32 v51, v2
	v_mov_b32_e32 v52, v2
	v_mov_b32_e32 v53, v2
	v_mov_b32_e32 v54, v2
	v_mov_b32_e32 v55, v2
	v_mov_b32_e32 v56, v2
	v_mov_b32_e32 v57, v2
	v_mov_b32_e32 v10, v2
	v_mov_b32_e32 v11, v2
	v_mov_b32_e32 v12, v2
	v_mov_b32_e32 v13, v2
	v_mov_b32_e32 v14, v2
	v_mov_b32_e32 v15, v2
	v_mov_b32_e32 v16, v2
	v_mov_b32_e32 v17, v2
	v_mov_b32_e32 v26, v2
	v_mov_b32_e32 v27, v2
	v_mov_b32_e32 v28, v2
	v_mov_b32_e32 v29, v2
	v_mov_b32_e32 v30, v2
	v_mov_b32_e32 v31, v2
	v_mov_b32_e32 v32, v2
	v_mov_b32_e32 v33, v2
	v_mov_b32_e32 v42, v2
	v_mov_b32_e32 v43, v2
	v_mov_b32_e32 v44, v2
	v_mov_b32_e32 v45, v2
	v_mov_b32_e32 v46, v2
	v_mov_b32_e32 v47, v2
	v_mov_b32_e32 v48, v2
	v_mov_b32_e32 v49, v2
	v_mov_b32_e32 v58, v2
	v_mov_b32_e32 v59, v2
	v_mov_b32_e32 v60, v2
	v_mov_b32_e32 v61, v2
	v_mov_b32_e32 v62, v2
	v_mov_b32_e32 v63, v2
	v_mov_b32_e32 v64, v2
	v_mov_b32_e32 v65, v2
	v_mov_b32_e32 v66, v2
	v_mov_b32_e32 v67, v2
	v_mov_b32_e32 v68, v2
	v_mov_b32_e32 v69, v2
	v_mov_b32_e32 v70, v2
	v_mov_b32_e32 v71, v2
	v_mov_b32_e32 v72, v2
	v_mov_b32_e32 v73, v2
	v_mov_b32_e32 v82, v2
	v_mov_b32_e32 v83, v2
	v_mov_b32_e32 v84, v2
	v_mov_b32_e32 v85, v2
	v_mov_b32_e32 v86, v2
	v_mov_b32_e32 v87, v2
	v_mov_b32_e32 v88, v2
	v_mov_b32_e32 v89, v2
	v_mov_b32_e32 v98, v2
	v_mov_b32_e32 v99, v2
	v_mov_b32_e32 v100, v2
	v_mov_b32_e32 v101, v2
	v_mov_b32_e32 v102, v2
	v_mov_b32_e32 v103, v2
	v_mov_b32_e32 v104, v2
	v_mov_b32_e32 v105, v2
	v_mov_b32_e32 v114, v2
	v_mov_b32_e32 v115, v2
	v_mov_b32_e32 v116, v2
	v_mov_b32_e32 v117, v2
	v_mov_b32_e32 v118, v2
	v_mov_b32_e32 v119, v2
	v_mov_b32_e32 v120, v2
	v_mov_b32_e32 v121, v2
	v_mov_b32_e32 v74, v2
	v_mov_b32_e32 v75, v2
	v_mov_b32_e32 v76, v2
	v_mov_b32_e32 v77, v2
	v_mov_b32_e32 v78, v2
	v_mov_b32_e32 v79, v2
	v_mov_b32_e32 v80, v2
	v_mov_b32_e32 v81, v2
	v_mov_b32_e32 v90, v2
	v_mov_b32_e32 v91, v2
	v_mov_b32_e32 v92, v2
	v_mov_b32_e32 v93, v2
	v_mov_b32_e32 v94, v2
	v_mov_b32_e32 v95, v2
	v_mov_b32_e32 v96, v2
	v_mov_b32_e32 v97, v2
	v_mov_b32_e32 v106, v2
	v_mov_b32_e32 v107, v2
	v_mov_b32_e32 v108, v2
	v_mov_b32_e32 v109, v2
	v_mov_b32_e32 v110, v2
	v_mov_b32_e32 v111, v2
	v_mov_b32_e32 v112, v2
	v_mov_b32_e32 v113, v2
	v_mov_b32_e32 v122, v2
	v_mov_b32_e32 v123, v2
	v_mov_b32_e32 v124, v2
	v_mov_b32_e32 v125, v2
	v_mov_b32_e32 v126, v2
	v_mov_b32_e32 v127, v2
	v_mov_b32_e32 v128, v2
	v_mov_b32_e32 v129, v2
	s_barrier
	.p2align 3

.LBB0_796:
	s_ashr_i32 s61, s60, 31
	s_lshl_b64 s[62:63], s[60:61], 20
	s_add_u32 s62, s24, s62
	s_addc_u32 s63, s25, s63
	s_and_b64 s[64:65], s[10:11], exec
	s_cselect_b32 s61, s63, s73
	s_cselect_b32 s67, s62, s72
	s_ashr_i32 s59, s58, 31
	s_lshl_b64 s[64:65], s[58:59], 20
	s_add_u32 s64, s38, s64
	s_addc_u32 s65, s39, s65
	s_and_b64 s[74:75], s[10:11], exec
	s_cselect_b32 s59, s65, s71
	s_cselect_b32 s76, s64, s70
	s_add_u32 s77, s70, 0x100
	s_addc_u32 s78, s71, 0
	s_add_u32 s70, s72, 0x80080
	v_mov_b32_e32 v2, 0
	s_addc_u32 s71, s73, 0
	s_mov_b32 s79, -2
	s_waitcnt lgkmcnt(0)
	v_mov_b32_e32 v3, v2
	v_mov_b32_e32 v4, v2
	v_mov_b32_e32 v5, v2
	v_mov_b32_e32 v6, v2
	v_mov_b32_e32 v7, v2
	v_mov_b32_e32 v8, v2
	v_mov_b32_e32 v9, v2
	v_mov_b32_e32 v18, v2
	v_mov_b32_e32 v19, v2
	v_mov_b32_e32 v20, v2
	v_mov_b32_e32 v21, v2
	v_mov_b32_e32 v22, v2
	v_mov_b32_e32 v23, v2
	v_mov_b32_e32 v24, v2
	v_mov_b32_e32 v25, v2
	v_mov_b32_e32 v34, v2
	v_mov_b32_e32 v35, v2
	v_mov_b32_e32 v36, v2
	v_mov_b32_e32 v37, v2
	v_mov_b32_e32 v38, v2
	v_mov_b32_e32 v39, v2
	v_mov_b32_e32 v40, v2
	v_mov_b32_e32 v41, v2
	v_mov_b32_e32 v50, v2
	v_mov_b32_e32 v51, v2
	v_mov_b32_e32 v52, v2
	v_mov_b32_e32 v53, v2
	v_mov_b32_e32 v54, v2
	v_mov_b32_e32 v55, v2
	v_mov_b32_e32 v56, v2
	v_mov_b32_e32 v57, v2
	v_mov_b32_e32 v10, v2
	v_mov_b32_e32 v11, v2
	v_mov_b32_e32 v12, v2
	v_mov_b32_e32 v13, v2
	v_mov_b32_e32 v14, v2
	v_mov_b32_e32 v15, v2
	v_mov_b32_e32 v16, v2
	v_mov_b32_e32 v17, v2
	v_mov_b32_e32 v26, v2
	v_mov_b32_e32 v27, v2
	v_mov_b32_e32 v28, v2
	v_mov_b32_e32 v29, v2
	v_mov_b32_e32 v30, v2
	v_mov_b32_e32 v31, v2
	v_mov_b32_e32 v32, v2
	v_mov_b32_e32 v33, v2
	v_mov_b32_e32 v42, v2
	v_mov_b32_e32 v43, v2
	v_mov_b32_e32 v44, v2
	v_mov_b32_e32 v45, v2
	v_mov_b32_e32 v46, v2
	v_mov_b32_e32 v47, v2
	v_mov_b32_e32 v48, v2
	v_mov_b32_e32 v49, v2
	v_mov_b32_e32 v58, v2
	v_mov_b32_e32 v59, v2
	v_mov_b32_e32 v60, v2
	v_mov_b32_e32 v61, v2
	v_mov_b32_e32 v62, v2
	v_mov_b32_e32 v63, v2
	v_mov_b32_e32 v64, v2
	v_mov_b32_e32 v65, v2
	v_mov_b32_e32 v66, v2
	v_mov_b32_e32 v67, v2
	v_mov_b32_e32 v68, v2
	v_mov_b32_e32 v69, v2
	v_mov_b32_e32 v70, v2
	v_mov_b32_e32 v71, v2
	v_mov_b32_e32 v72, v2
	v_mov_b32_e32 v73, v2
	v_mov_b32_e32 v82, v2
	v_mov_b32_e32 v83, v2
	v_mov_b32_e32 v84, v2
	v_mov_b32_e32 v85, v2
	v_mov_b32_e32 v86, v2
	v_mov_b32_e32 v87, v2
	v_mov_b32_e32 v88, v2
	v_mov_b32_e32 v89, v2
	v_mov_b32_e32 v98, v2
	v_mov_b32_e32 v99, v2
	v_mov_b32_e32 v100, v2
	v_mov_b32_e32 v101, v2
	v_mov_b32_e32 v102, v2
	v_mov_b32_e32 v103, v2
	v_mov_b32_e32 v104, v2
	v_mov_b32_e32 v105, v2
	v_mov_b32_e32 v114, v2
	v_mov_b32_e32 v115, v2
	v_mov_b32_e32 v116, v2
	v_mov_b32_e32 v117, v2
	v_mov_b32_e32 v118, v2
	v_mov_b32_e32 v119, v2
	v_mov_b32_e32 v120, v2
	v_mov_b32_e32 v121, v2
	v_mov_b32_e32 v74, v2
	v_mov_b32_e32 v75, v2
	v_mov_b32_e32 v76, v2
	v_mov_b32_e32 v77, v2
	v_mov_b32_e32 v78, v2
	v_mov_b32_e32 v79, v2
	v_mov_b32_e32 v80, v2
	v_mov_b32_e32 v81, v2
	v_mov_b32_e32 v90, v2
	v_mov_b32_e32 v91, v2
	v_mov_b32_e32 v92, v2
	v_mov_b32_e32 v93, v2
	v_mov_b32_e32 v94, v2
	v_mov_b32_e32 v95, v2
	v_mov_b32_e32 v96, v2
	v_mov_b32_e32 v97, v2
	v_mov_b32_e32 v106, v2
	v_mov_b32_e32 v107, v2
	v_mov_b32_e32 v108, v2
	v_mov_b32_e32 v109, v2
	v_mov_b32_e32 v110, v2
	v_mov_b32_e32 v111, v2
	v_mov_b32_e32 v112, v2
	v_mov_b32_e32 v113, v2
	v_mov_b32_e32 v122, v2
	v_mov_b32_e32 v123, v2
	v_mov_b32_e32 v124, v2
	v_mov_b32_e32 v125, v2
	v_mov_b32_e32 v126, v2
	v_mov_b32_e32 v127, v2
	v_mov_b32_e32 v128, v2
	v_mov_b32_e32 v129, v2
	.p2align 3

.LBB0_847:
	s_ashr_i32 s59, s58, 31
	s_lshl_b64 s[62:63], s[58:59], 20
	s_add_u32 s62, s0, s62
	s_addc_u32 s63, s1, s63
	s_and_b64 s[64:65], s[10:11], exec
	s_cselect_b32 s13, s63, s71
	s_cselect_b32 s59, s62, s70
	s_ashr_i32 s61, s60, 31
	s_lshl_b64 s[64:65], s[60:61], 20
	s_add_u32 s64, s33, s64
	s_addc_u32 s65, s48, s65
	s_and_b64 s[10:11], s[10:11], exec
	s_cselect_b32 s61, s65, s69
	s_cselect_b32 s67, s64, s68
	s_add_u32 s79, s68, 0x100
	s_addc_u32 s80, s69, 0
	s_add_u32 s10, s70, 0x80080
	v_mov_b32_e32 v2, 0
	s_addc_u32 s11, s71, 0
	s_mov_b32 s81, -2
	v_mov_b32_e32 v3, v2
	v_mov_b32_e32 v4, v2
	v_mov_b32_e32 v5, v2
	v_mov_b32_e32 v6, v2
	v_mov_b32_e32 v7, v2
	v_mov_b32_e32 v8, v2
	v_mov_b32_e32 v9, v2
	v_mov_b32_e32 v18, v2
	v_mov_b32_e32 v19, v2
	v_mov_b32_e32 v20, v2
	v_mov_b32_e32 v21, v2
	v_mov_b32_e32 v22, v2
	v_mov_b32_e32 v23, v2
	v_mov_b32_e32 v24, v2
	v_mov_b32_e32 v25, v2
	v_mov_b32_e32 v34, v2
	v_mov_b32_e32 v35, v2
	v_mov_b32_e32 v36, v2
	v_mov_b32_e32 v37, v2
	v_mov_b32_e32 v38, v2
	v_mov_b32_e32 v39, v2
	v_mov_b32_e32 v40, v2
	v_mov_b32_e32 v41, v2
	v_mov_b32_e32 v50, v2
	v_mov_b32_e32 v51, v2
	v_mov_b32_e32 v52, v2
	v_mov_b32_e32 v53, v2
	v_mov_b32_e32 v54, v2
	v_mov_b32_e32 v55, v2
	v_mov_b32_e32 v56, v2
	v_mov_b32_e32 v57, v2
	v_mov_b32_e32 v10, v2
	v_mov_b32_e32 v11, v2
	v_mov_b32_e32 v12, v2
	v_mov_b32_e32 v13, v2
	v_mov_b32_e32 v14, v2
	v_mov_b32_e32 v15, v2
	v_mov_b32_e32 v16, v2
	v_mov_b32_e32 v17, v2
	v_mov_b32_e32 v26, v2
	v_mov_b32_e32 v27, v2
	v_mov_b32_e32 v28, v2
	v_mov_b32_e32 v29, v2
	v_mov_b32_e32 v30, v2
	v_mov_b32_e32 v31, v2
	v_mov_b32_e32 v32, v2
	v_mov_b32_e32 v33, v2
	v_mov_b32_e32 v42, v2
	v_mov_b32_e32 v43, v2
	v_mov_b32_e32 v44, v2
	v_mov_b32_e32 v45, v2
	v_mov_b32_e32 v46, v2
	v_mov_b32_e32 v47, v2
	v_mov_b32_e32 v48, v2
	v_mov_b32_e32 v49, v2
	v_mov_b32_e32 v58, v2
	v_mov_b32_e32 v59, v2
	v_mov_b32_e32 v60, v2
	v_mov_b32_e32 v61, v2
	v_mov_b32_e32 v62, v2
	v_mov_b32_e32 v63, v2
	v_mov_b32_e32 v64, v2
	v_mov_b32_e32 v65, v2
	v_mov_b32_e32 v66, v2
	v_mov_b32_e32 v67, v2
	v_mov_b32_e32 v68, v2
	v_mov_b32_e32 v69, v2
	v_mov_b32_e32 v70, v2
	v_mov_b32_e32 v71, v2
	v_mov_b32_e32 v72, v2
	v_mov_b32_e32 v73, v2
	v_mov_b32_e32 v82, v2
	v_mov_b32_e32 v83, v2
	v_mov_b32_e32 v84, v2
	v_mov_b32_e32 v85, v2
	v_mov_b32_e32 v86, v2
	v_mov_b32_e32 v87, v2
	v_mov_b32_e32 v88, v2
	v_mov_b32_e32 v89, v2
	v_mov_b32_e32 v98, v2
	v_mov_b32_e32 v99, v2
	v_mov_b32_e32 v100, v2
	v_mov_b32_e32 v101, v2
	v_mov_b32_e32 v102, v2
	v_mov_b32_e32 v103, v2
	v_mov_b32_e32 v104, v2
	v_mov_b32_e32 v105, v2
	v_mov_b32_e32 v114, v2
	v_mov_b32_e32 v115, v2
	v_mov_b32_e32 v116, v2
	v_mov_b32_e32 v117, v2
	v_mov_b32_e32 v118, v2
	v_mov_b32_e32 v119, v2
	v_mov_b32_e32 v120, v2
	v_mov_b32_e32 v121, v2
	v_mov_b32_e32 v74, v2
	v_mov_b32_e32 v75, v2
	v_mov_b32_e32 v76, v2
	v_mov_b32_e32 v77, v2
	v_mov_b32_e32 v78, v2
	v_mov_b32_e32 v79, v2
	v_mov_b32_e32 v80, v2
	v_mov_b32_e32 v81, v2
	v_mov_b32_e32 v90, v2
	v_mov_b32_e32 v91, v2
	v_mov_b32_e32 v92, v2
	v_mov_b32_e32 v93, v2
	v_mov_b32_e32 v94, v2
	v_mov_b32_e32 v95, v2
	v_mov_b32_e32 v96, v2
	v_mov_b32_e32 v97, v2
	v_mov_b32_e32 v106, v2
	v_mov_b32_e32 v107, v2
	v_mov_b32_e32 v108, v2
	v_mov_b32_e32 v109, v2
	v_mov_b32_e32 v110, v2
	v_mov_b32_e32 v111, v2
	v_mov_b32_e32 v112, v2
	v_mov_b32_e32 v113, v2
	v_mov_b32_e32 v122, v2
	v_mov_b32_e32 v123, v2
	v_mov_b32_e32 v124, v2
	v_mov_b32_e32 v125, v2
	v_mov_b32_e32 v126, v2
	v_mov_b32_e32 v127, v2
	v_mov_b32_e32 v128, v2
	v_mov_b32_e32 v129, v2
	.p2align 3

.LBB0_1128:
	v_lshl_or_b32 v140, s21, 6, v1
	s_lshl_b32 s21, s21, 13
	s_lshl_b32 s20, s20, 5
	v_bitop3_b32 v10, v166, s21, v139 bitop3:0xde
	s_and_b32 s25, s20, 0x60
	s_mov_b64 s[20:21], 0x80
	s_add_i32 m0, s1, 0x18000
	v_lshl_add_u64 v[2:3], v[2:3], 0, s[20:21]
	s_waitcnt vmcnt(2)
	s_barrier
	global_load_lds_dwordx4 v[2:3], off
	v_lshl_add_u64 v[2:3], v[4:5], 0, s[20:21]
	s_add_i32 m0, s1, 0x1a000
	s_add_i32 s37, s1, 0x8000
	s_add_i32 s38, s1, 0xa000
	global_load_lds_dwordx4 v[2:3], off
	v_lshl_add_u64 v[2:3], v[8:9], 0, s[20:21]
	s_mov_b32 m0, s37
	s_add_u32 s34, s12, 0x80080
	global_load_lds_dwordx4 v[2:3], off
	v_lshl_add_u64 v[2:3], v[6:7], 0, s[20:21]
	s_mov_b32 m0, s38
	s_addc_u32 s35, s13, 0
	global_load_lds_dwordx4 v[2:3], off
	s_add_i32 m0, s1, 0x1c000
	v_lshl_add_u64 v[2:3], s[34:35], 0, v[130:131]
	global_load_lds_dwordx4 v[2:3], off
	v_lshl_add_u64 v[2:3], s[34:35], 0, v[132:133]
	s_add_i32 m0, s1, 0x1e000
	s_add_u32 s28, s10, s28
	global_load_lds_dwordx4 v[2:3], off
	s_addc_u32 s29, s11, s29
	s_add_u32 s39, s28, 0x5b00100
	s_addc_u32 s40, s29, 0
	s_add_u32 s22, s10, s22
	s_addc_u32 s23, s11, s23
	v_lshl_add_u64 v[2:3], s[22:23], 0, v[134:135]
	s_mov_b64 s[28:29], 0x10a80080
	v_lshl_or_b32 v11, s25, 7, v167
	s_waitcnt vmcnt(6)
	v_lshl_add_u64 v[134:135], v[2:3], 0, s[28:29]
	v_lshl_add_u64 v[2:3], s[22:23], 0, v[136:137]
	v_lshl_add_u64 v[136:137], v[2:3], 0, s[28:29]
	v_mov_b32_e32 v2, 0
	v_add_u32_e32 v139, s3, v11
	v_add_u32_e32 v141, s45, v11
	s_add_i32 s3, s3, s30
	s_add_i32 s45, s45, s30
	v_add_u32_e32 v143, s47, v11
	s_add_i32 s47, s47, s30
	s_add_i32 s49, s72, s30
	s_mov_b32 s41, -2
	s_mov_b64 s[28:29], 0
	v_add_u32_e32 v142, 0, v10
	s_add_i32 s42, s1, 0xc000
	s_add_i32 s43, s1, 0xe000
	s_add_i32 s44, s3, 0x2000
	s_add_i32 s46, s45, 0x2000
	v_add_u32_e32 v144, s72, v11
	s_add_i32 s48, s47, 0x2000
	s_add_i32 s51, s49, 0x2000
	v_mov_b32_e32 v3, v2
	v_mov_b32_e32 v4, v2
	v_mov_b32_e32 v5, v2
	v_mov_b32_e32 v6, v2
	v_mov_b32_e32 v7, v2
	v_mov_b32_e32 v8, v2
	v_mov_b32_e32 v9, v2
	v_mov_b32_e32 v18, v2
	v_mov_b32_e32 v19, v2
	v_mov_b32_e32 v20, v2
	v_mov_b32_e32 v21, v2
	v_mov_b32_e32 v22, v2
	v_mov_b32_e32 v23, v2
	v_mov_b32_e32 v24, v2
	v_mov_b32_e32 v25, v2
	v_mov_b32_e32 v34, v2
	v_mov_b32_e32 v35, v2
	v_mov_b32_e32 v36, v2
	v_mov_b32_e32 v37, v2
	v_mov_b32_e32 v38, v2
	v_mov_b32_e32 v39, v2
	v_mov_b32_e32 v40, v2
	v_mov_b32_e32 v41, v2
	v_mov_b32_e32 v50, v2
	v_mov_b32_e32 v51, v2
	v_mov_b32_e32 v52, v2
	v_mov_b32_e32 v53, v2
	v_mov_b32_e32 v54, v2
	v_mov_b32_e32 v55, v2
	v_mov_b32_e32 v56, v2
	v_mov_b32_e32 v57, v2
	v_mov_b32_e32 v10, v2
	v_mov_b32_e32 v11, v2
	v_mov_b32_e32 v12, v2
	v_mov_b32_e32 v13, v2
	v_mov_b32_e32 v14, v2
	v_mov_b32_e32 v15, v2
	v_mov_b32_e32 v16, v2
	v_mov_b32_e32 v17, v2
	v_mov_b32_e32 v26, v2
	v_mov_b32_e32 v27, v2
	v_mov_b32_e32 v28, v2
	v_mov_b32_e32 v29, v2
	v_mov_b32_e32 v30, v2
	v_mov_b32_e32 v31, v2
	v_mov_b32_e32 v32, v2
	v_mov_b32_e32 v33, v2
	v_mov_b32_e32 v42, v2
	v_mov_b32_e32 v43, v2
	v_mov_b32_e32 v44, v2
	v_mov_b32_e32 v45, v2
	v_mov_b32_e32 v46, v2
	v_mov_b32_e32 v47, v2
	v_mov_b32_e32 v48, v2
	v_mov_b32_e32 v49, v2
	v_mov_b32_e32 v58, v2
	v_mov_b32_e32 v59, v2
	v_mov_b32_e32 v60, v2
	v_mov_b32_e32 v61, v2
	v_mov_b32_e32 v62, v2
	v_mov_b32_e32 v63, v2
	v_mov_b32_e32 v64, v2
	v_mov_b32_e32 v65, v2
	v_mov_b32_e32 v66, v2
	v_mov_b32_e32 v67, v2
	v_mov_b32_e32 v68, v2
	v_mov_b32_e32 v69, v2
	v_mov_b32_e32 v70, v2
	v_mov_b32_e32 v71, v2
	v_mov_b32_e32 v72, v2
	v_mov_b32_e32 v73, v2
	v_mov_b32_e32 v82, v2
	v_mov_b32_e32 v83, v2
	v_mov_b32_e32 v84, v2
	v_mov_b32_e32 v85, v2
	v_mov_b32_e32 v86, v2
	v_mov_b32_e32 v87, v2
	v_mov_b32_e32 v88, v2
	v_mov_b32_e32 v89, v2
	v_mov_b32_e32 v98, v2
	v_mov_b32_e32 v99, v2
	v_mov_b32_e32 v100, v2
	v_mov_b32_e32 v101, v2
	v_mov_b32_e32 v102, v2
	v_mov_b32_e32 v103, v2
	v_mov_b32_e32 v104, v2
	v_mov_b32_e32 v105, v2
	v_mov_b32_e32 v114, v2
	v_mov_b32_e32 v115, v2
	v_mov_b32_e32 v116, v2
	v_mov_b32_e32 v117, v2
	v_mov_b32_e32 v118, v2
	v_mov_b32_e32 v119, v2
	v_mov_b32_e32 v120, v2
	v_mov_b32_e32 v121, v2
	v_mov_b32_e32 v74, v2
	v_mov_b32_e32 v75, v2
	v_mov_b32_e32 v76, v2
	v_mov_b32_e32 v77, v2
	v_mov_b32_e32 v78, v2
	v_mov_b32_e32 v79, v2
	v_mov_b32_e32 v80, v2
	v_mov_b32_e32 v81, v2
	v_mov_b32_e32 v90, v2
	v_mov_b32_e32 v91, v2
	v_mov_b32_e32 v92, v2
	v_mov_b32_e32 v93, v2
	v_mov_b32_e32 v94, v2
	v_mov_b32_e32 v95, v2
	v_mov_b32_e32 v96, v2
	v_mov_b32_e32 v97, v2
	v_mov_b32_e32 v106, v2
	v_mov_b32_e32 v107, v2
	v_mov_b32_e32 v108, v2
	v_mov_b32_e32 v109, v2
	v_mov_b32_e32 v110, v2
	v_mov_b32_e32 v111, v2
	v_mov_b32_e32 v112, v2
	v_mov_b32_e32 v113, v2
	v_mov_b32_e32 v122, v2
	v_mov_b32_e32 v123, v2
	v_mov_b32_e32 v124, v2
	v_mov_b32_e32 v125, v2
	v_mov_b32_e32 v126, v2
	v_mov_b32_e32 v127, v2
	v_mov_b32_e32 v128, v2
	v_mov_b32_e32 v129, v2
	s_barrier
	.p2align 3

.LBB0_1493:
	s_ashr_i32 s61, s60, 31
	s_lshl_b64 s[62:63], s[60:61], 20
	s_add_u32 s62, s24, s62
	s_addc_u32 s63, s25, s63
	s_and_b64 s[64:65], s[6:7], exec
	s_cselect_b32 s9, s63, s69
	s_cselect_b32 s11, s62, s68
	s_ashr_i32 s59, s58, 31
	s_lshl_b64 s[64:65], s[58:59], 20
	s_add_u32 s64, s26, s64
	s_addc_u32 s65, s27, s65
	s_and_b64 s[70:71], s[6:7], exec
	s_cselect_b32 s59, s65, s67
	s_cselect_b32 s61, s64, s66
	s_add_u32 s73, s66, 0x100
	s_addc_u32 s74, s67, 0
	s_add_u32 s66, s68, 0x80080
	v_mov_b32_e32 v2, 0
	s_addc_u32 s67, s69, 0
	s_mov_b32 s75, -2
	v_mov_b32_e32 v3, v2
	v_mov_b32_e32 v4, v2
	v_mov_b32_e32 v5, v2
	v_mov_b32_e32 v6, v2
	v_mov_b32_e32 v7, v2
	v_mov_b32_e32 v8, v2
	v_mov_b32_e32 v9, v2
	v_mov_b32_e32 v18, v2
	v_mov_b32_e32 v19, v2
	v_mov_b32_e32 v20, v2
	v_mov_b32_e32 v21, v2
	v_mov_b32_e32 v22, v2
	v_mov_b32_e32 v23, v2
	v_mov_b32_e32 v24, v2
	v_mov_b32_e32 v25, v2
	v_mov_b32_e32 v34, v2
	v_mov_b32_e32 v35, v2
	v_mov_b32_e32 v36, v2
	v_mov_b32_e32 v37, v2
	v_mov_b32_e32 v38, v2
	v_mov_b32_e32 v39, v2
	v_mov_b32_e32 v40, v2
	v_mov_b32_e32 v41, v2
	v_mov_b32_e32 v50, v2
	v_mov_b32_e32 v51, v2
	v_mov_b32_e32 v52, v2
	v_mov_b32_e32 v53, v2
	v_mov_b32_e32 v54, v2
	v_mov_b32_e32 v55, v2
	v_mov_b32_e32 v56, v2
	v_mov_b32_e32 v57, v2
	v_mov_b32_e32 v10, v2
	v_mov_b32_e32 v11, v2
	v_mov_b32_e32 v12, v2
	v_mov_b32_e32 v13, v2
	v_mov_b32_e32 v14, v2
	v_mov_b32_e32 v15, v2
	v_mov_b32_e32 v16, v2
	v_mov_b32_e32 v17, v2
	v_mov_b32_e32 v26, v2
	v_mov_b32_e32 v27, v2
	v_mov_b32_e32 v28, v2
	v_mov_b32_e32 v29, v2
	v_mov_b32_e32 v30, v2
	v_mov_b32_e32 v31, v2
	v_mov_b32_e32 v32, v2
	v_mov_b32_e32 v33, v2
	v_mov_b32_e32 v42, v2
	v_mov_b32_e32 v43, v2
	v_mov_b32_e32 v44, v2
	v_mov_b32_e32 v45, v2
	v_mov_b32_e32 v46, v2
	v_mov_b32_e32 v47, v2
	v_mov_b32_e32 v48, v2
	v_mov_b32_e32 v49, v2
	v_mov_b32_e32 v58, v2
	v_mov_b32_e32 v59, v2
	v_mov_b32_e32 v60, v2
	v_mov_b32_e32 v61, v2
	v_mov_b32_e32 v62, v2
	v_mov_b32_e32 v63, v2
	v_mov_b32_e32 v64, v2
	v_mov_b32_e32 v65, v2
	v_mov_b32_e32 v66, v2
	v_mov_b32_e32 v67, v2
	v_mov_b32_e32 v68, v2
	v_mov_b32_e32 v69, v2
	v_mov_b32_e32 v70, v2
	v_mov_b32_e32 v71, v2
	v_mov_b32_e32 v72, v2
	v_mov_b32_e32 v73, v2
	v_mov_b32_e32 v82, v2
	v_mov_b32_e32 v83, v2
	v_mov_b32_e32 v84, v2
	v_mov_b32_e32 v85, v2
	v_mov_b32_e32 v86, v2
	v_mov_b32_e32 v87, v2
	v_mov_b32_e32 v88, v2
	v_mov_b32_e32 v89, v2
	v_mov_b32_e32 v98, v2
	v_mov_b32_e32 v99, v2
	v_mov_b32_e32 v100, v2
	v_mov_b32_e32 v101, v2
	v_mov_b32_e32 v102, v2
	v_mov_b32_e32 v103, v2
	v_mov_b32_e32 v104, v2
	v_mov_b32_e32 v105, v2
	v_mov_b32_e32 v114, v2
	v_mov_b32_e32 v115, v2
	v_mov_b32_e32 v116, v2
	v_mov_b32_e32 v117, v2
	v_mov_b32_e32 v118, v2
	v_mov_b32_e32 v119, v2
	v_mov_b32_e32 v120, v2
	v_mov_b32_e32 v121, v2
	v_mov_b32_e32 v74, v2
	v_mov_b32_e32 v75, v2
	v_mov_b32_e32 v76, v2
	v_mov_b32_e32 v77, v2
	v_mov_b32_e32 v78, v2
	v_mov_b32_e32 v79, v2
	v_mov_b32_e32 v80, v2
	v_mov_b32_e32 v81, v2
	v_mov_b32_e32 v90, v2
	v_mov_b32_e32 v91, v2
	v_mov_b32_e32 v92, v2
	v_mov_b32_e32 v93, v2
	v_mov_b32_e32 v94, v2
	v_mov_b32_e32 v95, v2
	v_mov_b32_e32 v96, v2
	v_mov_b32_e32 v97, v2
	v_mov_b32_e32 v106, v2
	v_mov_b32_e32 v107, v2
	v_mov_b32_e32 v108, v2
	v_mov_b32_e32 v109, v2
	v_mov_b32_e32 v110, v2
	v_mov_b32_e32 v111, v2
	v_mov_b32_e32 v112, v2
	v_mov_b32_e32 v113, v2
	v_mov_b32_e32 v122, v2
	v_mov_b32_e32 v123, v2
	v_mov_b32_e32 v124, v2
	v_mov_b32_e32 v125, v2
	v_mov_b32_e32 v126, v2
	v_mov_b32_e32 v127, v2
	v_mov_b32_e32 v128, v2
	v_mov_b32_e32 v129, v2
	.p2align 3

.LBB0_2755:
	s_ashr_i32 s41, s40, 31
	s_lshl_b64 s[42:43], s[40:41], 20
	s_add_u32 s42, s22, s42
	s_addc_u32 s43, s23, s43
	s_and_b64 s[44:45], s[8:9], exec
	s_cselect_b32 s41, s43, s63
	s_cselect_b32 s47, s42, s62
	s_ashr_i32 s39, s38, 31
	s_lshl_b64 s[44:45], s[38:39], 20
	s_add_u32 s44, s24, s44
	s_addc_u32 s45, s25, s45
	s_and_b64 s[64:65], s[8:9], exec
	s_cselect_b32 s39, s45, s61
	s_cselect_b32 s59, s44, s60
	s_add_u32 s66, s60, 0x100
	s_addc_u32 s67, s61, 0
	s_add_u32 s60, s62, 0x80080
	v_mov_b32_e32 v2, 0
	s_addc_u32 s61, s63, 0
	s_mov_b32 s68, -2
	s_waitcnt lgkmcnt(0)
	v_mov_b32_e32 v3, v2
	v_mov_b32_e32 v4, v2
	v_mov_b32_e32 v5, v2
	v_mov_b32_e32 v6, v2
	v_mov_b32_e32 v7, v2
	v_mov_b32_e32 v8, v2
	v_mov_b32_e32 v9, v2
	v_mov_b32_e32 v18, v2
	v_mov_b32_e32 v19, v2
	v_mov_b32_e32 v20, v2
	v_mov_b32_e32 v21, v2
	v_mov_b32_e32 v22, v2
	v_mov_b32_e32 v23, v2
	v_mov_b32_e32 v24, v2
	v_mov_b32_e32 v25, v2
	v_mov_b32_e32 v34, v2
	v_mov_b32_e32 v35, v2
	v_mov_b32_e32 v36, v2
	v_mov_b32_e32 v37, v2
	v_mov_b32_e32 v38, v2
	v_mov_b32_e32 v39, v2
	v_mov_b32_e32 v40, v2
	v_mov_b32_e32 v41, v2
	v_mov_b32_e32 v50, v2
	v_mov_b32_e32 v51, v2
	v_mov_b32_e32 v52, v2
	v_mov_b32_e32 v53, v2
	v_mov_b32_e32 v54, v2
	v_mov_b32_e32 v55, v2
	v_mov_b32_e32 v56, v2
	v_mov_b32_e32 v57, v2
	v_mov_b32_e32 v10, v2
	v_mov_b32_e32 v11, v2
	v_mov_b32_e32 v12, v2
	v_mov_b32_e32 v13, v2
	v_mov_b32_e32 v14, v2
	v_mov_b32_e32 v15, v2
	v_mov_b32_e32 v16, v2
	v_mov_b32_e32 v17, v2
	v_mov_b32_e32 v26, v2
	v_mov_b32_e32 v27, v2
	v_mov_b32_e32 v28, v2
	v_mov_b32_e32 v29, v2
	v_mov_b32_e32 v30, v2
	v_mov_b32_e32 v31, v2
	v_mov_b32_e32 v32, v2
	v_mov_b32_e32 v33, v2
	v_mov_b32_e32 v42, v2
	v_mov_b32_e32 v43, v2
	v_mov_b32_e32 v44, v2
	v_mov_b32_e32 v45, v2
	v_mov_b32_e32 v46, v2
	v_mov_b32_e32 v47, v2
	v_mov_b32_e32 v48, v2
	v_mov_b32_e32 v49, v2
	v_mov_b32_e32 v58, v2
	v_mov_b32_e32 v59, v2
	v_mov_b32_e32 v60, v2
	v_mov_b32_e32 v61, v2
	v_mov_b32_e32 v62, v2
	v_mov_b32_e32 v63, v2
	v_mov_b32_e32 v64, v2
	v_mov_b32_e32 v65, v2
	v_mov_b32_e32 v66, v2
	v_mov_b32_e32 v67, v2
	v_mov_b32_e32 v68, v2
	v_mov_b32_e32 v69, v2
	v_mov_b32_e32 v70, v2
	v_mov_b32_e32 v71, v2
	v_mov_b32_e32 v72, v2
	v_mov_b32_e32 v73, v2
	v_mov_b32_e32 v82, v2
	v_mov_b32_e32 v83, v2
	v_mov_b32_e32 v84, v2
	v_mov_b32_e32 v85, v2
	v_mov_b32_e32 v86, v2
	v_mov_b32_e32 v87, v2
	v_mov_b32_e32 v88, v2
	v_mov_b32_e32 v89, v2
	v_mov_b32_e32 v98, v2
	v_mov_b32_e32 v99, v2
	v_mov_b32_e32 v100, v2
	v_mov_b32_e32 v101, v2
	v_mov_b32_e32 v102, v2
	v_mov_b32_e32 v103, v2
	v_mov_b32_e32 v104, v2
	v_mov_b32_e32 v105, v2
	v_mov_b32_e32 v114, v2
	v_mov_b32_e32 v115, v2
	v_mov_b32_e32 v116, v2
	v_mov_b32_e32 v117, v2
	v_mov_b32_e32 v118, v2
	v_mov_b32_e32 v119, v2
	v_mov_b32_e32 v120, v2
	v_mov_b32_e32 v121, v2
	v_mov_b32_e32 v74, v2
	v_mov_b32_e32 v75, v2
	v_mov_b32_e32 v76, v2
	v_mov_b32_e32 v77, v2
	v_mov_b32_e32 v78, v2
	v_mov_b32_e32 v79, v2
	v_mov_b32_e32 v80, v2
	v_mov_b32_e32 v81, v2
	v_mov_b32_e32 v90, v2
	v_mov_b32_e32 v91, v2
	v_mov_b32_e32 v92, v2
	v_mov_b32_e32 v93, v2
	v_mov_b32_e32 v94, v2
	v_mov_b32_e32 v95, v2
	v_mov_b32_e32 v96, v2
	v_mov_b32_e32 v97, v2
	v_mov_b32_e32 v106, v2
	v_mov_b32_e32 v107, v2
	v_mov_b32_e32 v108, v2
	v_mov_b32_e32 v109, v2
	v_mov_b32_e32 v110, v2
	v_mov_b32_e32 v111, v2
	v_mov_b32_e32 v112, v2
	v_mov_b32_e32 v113, v2
	v_mov_b32_e32 v122, v2
	v_mov_b32_e32 v123, v2
	v_mov_b32_e32 v124, v2
	v_mov_b32_e32 v125, v2
	v_mov_b32_e32 v126, v2
	v_mov_b32_e32 v127, v2
	v_mov_b32_e32 v128, v2
	v_mov_b32_e32 v129, v2
	.p2align 3

.LBB0_2837:
	s_lshl_b32 s0, s0, 5
	v_lshlrev_b32_e32 v13, 6, v0
	s_mov_b64 s[16:17], 0x80
	v_lshlrev_b32_e32 v11, 1, v161
	v_lshlrev_b32_e32 v12, 2, v0
	s_and_b32 s27, s0, 0x60
	v_and_b32_e32 v205, 0x3c0, v13
	s_add_i32 m0, s21, 0x18000
	v_lshl_add_u64 v[8:9], v[8:9], 0, s[16:17]
	v_lshl_or_b32 v134, s1, 6, v1
	s_lshl_b32 s1, s1, 13
	v_and_b32_e32 v204, 32, v12
	v_or_b32_e32 v13, v11, v205
	s_lshl_b32 s0, s27, 7
	s_waitcnt vmcnt(2)
	s_barrier
	global_load_lds_dwordx4 v[8:9], off
	v_lshl_add_u64 v[6:7], v[6:7], 0, s[16:17]
	s_add_i32 m0, s21, 0x1a000
	s_add_i32 s43, s21, 0x8000
	s_add_i32 s44, s21, 0xa000
	v_lshl_or_b32 v165, v1, 6, v11
	v_bitop3_b32 v169, v11, v204, v205 bitop3:0x36
	v_bitop3_b32 v11, s0, v13, v204 bitop3:0xf6
	global_load_lds_dwordx4 v[6:7], off
	v_lshl_add_u64 v[4:5], v[4:5], 0, s[16:17]
	s_mov_b32 m0, s43
	s_add_u32 s0, s10, 0x80080
	v_bitop3_b32 v12, v165, s1, v204 bitop3:0xde
	global_load_lds_dwordx4 v[4:5], off
	v_lshl_add_u64 v[2:3], v[2:3], 0, s[16:17]
	s_mov_b32 m0, s44
	s_addc_u32 s1, s11, 0
	global_load_lds_dwordx4 v[2:3], off
	s_add_i32 m0, s21, 0x1c000
	v_lshl_add_u64 v[2:3], s[0:1], 0, v[150:151]
	global_load_lds_dwordx4 v[2:3], off
	v_lshl_add_u64 v[2:3], s[0:1], 0, v[146:147]
	s_add_i32 m0, s21, 0x1e000
	s_add_u32 s0, s18, s30
	global_load_lds_dwordx4 v[2:3], off
	s_addc_u32 s1, s19, s31
	s_add_u32 s45, s0, 0x6f00100
	v_lshrrev_b32_e32 v206, 11, v10
	s_addc_u32 s46, s1, 0
	v_lshlrev_b32_e32 v2, 16, v206
	v_lshlrev_b32_e32 v4, 12, v203
	v_or3_b32 v2, v185, v2, v4
	s_add_u32 s28, s18, s28
	v_add_u32_e32 v154, v2, v202
	v_mov_b32_e32 v155, v151
	s_addc_u32 s29, s19, s29
	v_lshl_add_u64 v[2:3], s[28:29], 0, v[154:155]
	s_mov_b64 s[0:1], 0x1e280080
	v_lshrrev_b32_e32 v207, 7, v0
	v_lshl_add_u64 v[130:131], v[2:3], 0, s[0:1]
	v_lshlrev_b32_e32 v2, 16, v207
	v_or3_b32 v2, v185, v2, v4
	v_add_u32_e32 v156, v2, v202
	v_mov_b32_e32 v157, v151
	v_lshl_add_u64 v[2:3], s[28:29], 0, v[156:157]
	s_waitcnt vmcnt(6)
	v_lshl_add_u64 v[132:133], v[2:3], 0, s[0:1]
	s_add_i32 s0, 0, 0x10000
	s_add_i32 s1, 0, 0x14000
	s_add_i32 s33, 0, 0x18000
	s_add_i32 s48, 0, 0x1c000
	s_add_i32 s58, s0, s34
	s_add_i32 s60, s1, s34
	s_add_i32 s62, s33, s34
	s_add_i32 s64, s48, s34
	s_mov_b32 s47, -2
	s_mov_b64 s[30:31], 0
	v_add_u32_e32 v135, s0, v11
	v_add_u32_e32 v136, s1, v11
	v_add_u32_e32 v137, 0, v12
	s_add_i32 s56, s21, 0xc000
	s_add_i32 s57, s21, 0xe000
	s_add_i32 s59, s58, 0x2000
	s_add_i32 s61, s60, 0x2000
	v_add_u32_e32 v138, s33, v11
	v_add_u32_e32 v139, s48, v11
	s_add_i32 s63, s62, 0x2000
	s_add_i32 s65, s64, 0x2000
	v_mov_b32_e32 v2, v151
	v_mov_b32_e32 v3, v151
	v_mov_b32_e32 v4, v151
	v_mov_b32_e32 v5, v151
	v_mov_b32_e32 v6, v151
	v_mov_b32_e32 v7, v151
	v_mov_b32_e32 v8, v151
	v_mov_b32_e32 v9, v151
	v_mov_b32_e32 v10, v151
	v_mov_b32_e32 v11, v151
	v_mov_b32_e32 v12, v151
	v_mov_b32_e32 v13, v151
	v_mov_b32_e32 v14, v151
	v_mov_b32_e32 v15, v151
	v_mov_b32_e32 v16, v151
	v_mov_b32_e32 v17, v151
	v_mov_b32_e32 v18, v151
	v_mov_b32_e32 v19, v151
	v_mov_b32_e32 v20, v151
	v_mov_b32_e32 v21, v151
	v_mov_b32_e32 v22, v151
	v_mov_b32_e32 v23, v151
	v_mov_b32_e32 v24, v151
	v_mov_b32_e32 v25, v151
	v_mov_b32_e32 v26, v151
	v_mov_b32_e32 v27, v151
	v_mov_b32_e32 v28, v151
	v_mov_b32_e32 v29, v151
	v_mov_b32_e32 v30, v151
	v_mov_b32_e32 v31, v151
	v_mov_b32_e32 v32, v151
	v_mov_b32_e32 v33, v151
	v_mov_b32_e32 v62, v151
	v_mov_b32_e32 v63, v151
	v_mov_b32_e32 v64, v151
	v_mov_b32_e32 v65, v151
	v_mov_b32_e32 v66, v151
	v_mov_b32_e32 v67, v151
	v_mov_b32_e32 v68, v151
	v_mov_b32_e32 v69, v151
	v_mov_b32_e32 v74, v151
	v_mov_b32_e32 v75, v151
	v_mov_b32_e32 v76, v151
	v_mov_b32_e32 v77, v151
	v_mov_b32_e32 v78, v151
	v_mov_b32_e32 v79, v151
	v_mov_b32_e32 v80, v151
	v_mov_b32_e32 v81, v151
	v_mov_b32_e32 v82, v151
	v_mov_b32_e32 v83, v151
	v_mov_b32_e32 v84, v151
	v_mov_b32_e32 v85, v151
	v_mov_b32_e32 v86, v151
	v_mov_b32_e32 v87, v151
	v_mov_b32_e32 v88, v151
	v_mov_b32_e32 v89, v151
	v_mov_b32_e32 v90, v151
	v_mov_b32_e32 v91, v151
	v_mov_b32_e32 v92, v151
	v_mov_b32_e32 v93, v151
	v_mov_b32_e32 v94, v151
	v_mov_b32_e32 v95, v151
	v_mov_b32_e32 v96, v151
	v_mov_b32_e32 v97, v151
	v_mov_b32_e32 v34, v151
	v_mov_b32_e32 v35, v151
	v_mov_b32_e32 v36, v151
	v_mov_b32_e32 v37, v151
	v_mov_b32_e32 v38, v151
	v_mov_b32_e32 v39, v151
	v_mov_b32_e32 v40, v151
	v_mov_b32_e32 v41, v151
	v_mov_b32_e32 v42, v151
	v_mov_b32_e32 v43, v151
	v_mov_b32_e32 v44, v151
	v_mov_b32_e32 v45, v151
	v_mov_b32_e32 v46, v151
	v_mov_b32_e32 v47, v151
	v_mov_b32_e32 v48, v151
	v_mov_b32_e32 v49, v151
	v_mov_b32_e32 v50, v151
	v_mov_b32_e32 v51, v151
	v_mov_b32_e32 v52, v151
	v_mov_b32_e32 v53, v151
	v_mov_b32_e32 v54, v151
	v_mov_b32_e32 v55, v151
	v_mov_b32_e32 v56, v151
	v_mov_b32_e32 v57, v151
	v_mov_b32_e32 v58, v151
	v_mov_b32_e32 v59, v151
	v_mov_b32_e32 v60, v151
	v_mov_b32_e32 v61, v151
	v_mov_b32_e32 v70, v151
	v_mov_b32_e32 v71, v151
	v_mov_b32_e32 v72, v151
	v_mov_b32_e32 v73, v151
	v_mov_b32_e32 v98, v151
	v_mov_b32_e32 v99, v151
	v_mov_b32_e32 v100, v151
	v_mov_b32_e32 v101, v151
	v_mov_b32_e32 v102, v151
	v_mov_b32_e32 v103, v151
	v_mov_b32_e32 v104, v151
	v_mov_b32_e32 v105, v151
	v_mov_b32_e32 v106, v151
	v_mov_b32_e32 v107, v151
	v_mov_b32_e32 v108, v151
	v_mov_b32_e32 v109, v151
	v_mov_b32_e32 v110, v151
	v_mov_b32_e32 v111, v151
	v_mov_b32_e32 v112, v151
	v_mov_b32_e32 v113, v151
	v_mov_b32_e32 v114, v151
	v_mov_b32_e32 v115, v151
	v_mov_b32_e32 v116, v151
	v_mov_b32_e32 v117, v151
	v_mov_b32_e32 v118, v151
	v_mov_b32_e32 v119, v151
	v_mov_b32_e32 v120, v151
	v_mov_b32_e32 v121, v151
	v_mov_b32_e32 v122, v151
	v_mov_b32_e32 v123, v151
	v_mov_b32_e32 v124, v151
	v_mov_b32_e32 v125, v151
	v_mov_b32_e32 v126, v151
	v_mov_b32_e32 v127, v151
	v_mov_b32_e32 v128, v151
	v_mov_b32_e32 v129, v151
	s_barrier
	.p2align 3

.LBB0_2868:
	s_ashr_i32 s35, s34, 31
	s_lshl_b64 s[38:39], s[34:35], 20
	s_add_u32 s38, s12, s38
	s_addc_u32 s39, s13, s39
	s_and_b64 s[40:41], s[60:61], exec
	s_cselect_b32 s35, s39, s59
	s_cselect_b32 s69, s38, s58
	s_ashr_i32 s37, s36, 31
	s_lshl_b64 s[40:41], s[36:37], 20
	s_add_u32 s40, s52, s40
	s_addc_u32 s41, s53, s41
	s_and_b64 s[60:61], s[60:61], exec
	s_cselect_b32 s37, s41, s47
	s_cselect_b32 s70, s40, s46
	s_add_u32 s71, s46, 0x100
	s_addc_u32 s72, s47, 0
	s_add_u32 s46, s58, 0x80080
	v_mov_b32_e32 v2, 0
	s_addc_u32 s47, s59, 0
	s_mov_b32 s73, -2
	v_mov_b32_e32 v3, v2
	v_mov_b32_e32 v4, v2
	v_mov_b32_e32 v5, v2
	v_mov_b32_e32 v6, v2
	v_mov_b32_e32 v7, v2
	v_mov_b32_e32 v8, v2
	v_mov_b32_e32 v9, v2
	v_mov_b32_e32 v10, v2
	v_mov_b32_e32 v11, v2
	v_mov_b32_e32 v12, v2
	v_mov_b32_e32 v13, v2
	v_mov_b32_e32 v14, v2
	v_mov_b32_e32 v15, v2
	v_mov_b32_e32 v16, v2
	v_mov_b32_e32 v17, v2
	v_mov_b32_e32 v18, v2
	v_mov_b32_e32 v19, v2
	v_mov_b32_e32 v20, v2
	v_mov_b32_e32 v21, v2
	v_mov_b32_e32 v22, v2
	v_mov_b32_e32 v23, v2
	v_mov_b32_e32 v24, v2
	v_mov_b32_e32 v25, v2
	v_mov_b32_e32 v26, v2
	v_mov_b32_e32 v27, v2
	v_mov_b32_e32 v28, v2
	v_mov_b32_e32 v29, v2
	v_mov_b32_e32 v30, v2
	v_mov_b32_e32 v31, v2
	v_mov_b32_e32 v32, v2
	v_mov_b32_e32 v33, v2
	v_mov_b32_e32 v62, v2
	v_mov_b32_e32 v63, v2
	v_mov_b32_e32 v64, v2
	v_mov_b32_e32 v65, v2
	v_mov_b32_e32 v66, v2
	v_mov_b32_e32 v67, v2
	v_mov_b32_e32 v68, v2
	v_mov_b32_e32 v69, v2
	v_mov_b32_e32 v74, v2
	v_mov_b32_e32 v75, v2
	v_mov_b32_e32 v76, v2
	v_mov_b32_e32 v77, v2
	v_mov_b32_e32 v78, v2
	v_mov_b32_e32 v79, v2
	v_mov_b32_e32 v80, v2
	v_mov_b32_e32 v81, v2
	v_mov_b32_e32 v82, v2
	v_mov_b32_e32 v83, v2
	v_mov_b32_e32 v84, v2
	v_mov_b32_e32 v85, v2
	v_mov_b32_e32 v86, v2
	v_mov_b32_e32 v87, v2
	v_mov_b32_e32 v88, v2
	v_mov_b32_e32 v89, v2
	v_mov_b32_e32 v90, v2
	v_mov_b32_e32 v91, v2
	v_mov_b32_e32 v92, v2
	v_mov_b32_e32 v93, v2
	v_mov_b32_e32 v94, v2
	v_mov_b32_e32 v95, v2
	v_mov_b32_e32 v96, v2
	v_mov_b32_e32 v97, v2
	v_mov_b32_e32 v34, v2
	v_mov_b32_e32 v35, v2
	v_mov_b32_e32 v36, v2
	v_mov_b32_e32 v37, v2
	v_mov_b32_e32 v38, v2
	v_mov_b32_e32 v39, v2
	v_mov_b32_e32 v40, v2
	v_mov_b32_e32 v41, v2
	v_mov_b32_e32 v42, v2
	v_mov_b32_e32 v43, v2
	v_mov_b32_e32 v44, v2
	v_mov_b32_e32 v45, v2
	v_mov_b32_e32 v46, v2
	v_mov_b32_e32 v47, v2
	v_mov_b32_e32 v48, v2
	v_mov_b32_e32 v49, v2
	v_mov_b32_e32 v50, v2
	v_mov_b32_e32 v51, v2
	v_mov_b32_e32 v52, v2
	v_mov_b32_e32 v53, v2
	v_mov_b32_e32 v54, v2
	v_mov_b32_e32 v55, v2
	v_mov_b32_e32 v56, v2
	v_mov_b32_e32 v57, v2
	v_mov_b32_e32 v58, v2
	v_mov_b32_e32 v59, v2
	v_mov_b32_e32 v60, v2
	v_mov_b32_e32 v61, v2
	v_mov_b32_e32 v70, v2
	v_mov_b32_e32 v71, v2
	v_mov_b32_e32 v72, v2
	v_mov_b32_e32 v73, v2
	v_mov_b32_e32 v98, v2
	v_mov_b32_e32 v99, v2
	v_mov_b32_e32 v100, v2
	v_mov_b32_e32 v101, v2
	v_mov_b32_e32 v102, v2
	v_mov_b32_e32 v103, v2
	v_mov_b32_e32 v104, v2
	v_mov_b32_e32 v105, v2
	v_mov_b32_e32 v106, v2
	v_mov_b32_e32 v107, v2
	v_mov_b32_e32 v108, v2
	v_mov_b32_e32 v109, v2
	v_mov_b32_e32 v110, v2
	v_mov_b32_e32 v111, v2
	v_mov_b32_e32 v112, v2
	v_mov_b32_e32 v113, v2
	v_mov_b32_e32 v114, v2
	v_mov_b32_e32 v115, v2
	v_mov_b32_e32 v116, v2
	v_mov_b32_e32 v117, v2
	v_mov_b32_e32 v118, v2
	v_mov_b32_e32 v119, v2
	v_mov_b32_e32 v120, v2
	v_mov_b32_e32 v121, v2
	v_mov_b32_e32 v122, v2
	v_mov_b32_e32 v123, v2
	v_mov_b32_e32 v124, v2
	v_mov_b32_e32 v125, v2
	v_mov_b32_e32 v126, v2
	v_mov_b32_e32 v127, v2
	v_mov_b32_e32 v128, v2
	v_mov_b32_e32 v129, v2
	.p2align 3

.LBB0_2911:
	s_ashr_i32 s37, s36, 31
	s_lshl_b64 s[38:39], s[36:37], 22
	s_add_u32 s38, s14, s38
	s_addc_u32 s39, s15, s39
	s_and_b64 s[40:41], s[60:61], exec
	s_cselect_b32 s37, s39, s59
	s_cselect_b32 s43, s38, s58
	s_ashr_i32 s35, s34, 31
	s_lshl_b64 s[40:41], s[34:35], 22
	s_add_u32 s40, s49, s40
	s_addc_u32 s41, s51, s41
	s_and_b64 s[60:61], s[60:61], exec
	s_cselect_b32 s35, s41, s47
	s_cselect_b32 s68, s40, s46
	s_add_u32 s69, s46, 0x100
	s_addc_u32 s70, s47, 0
	s_add_u32 s46, s58, 0x200080
	v_mov_b32_e32 v2, 0
	s_addc_u32 s47, s59, 0
	s_mov_b32 s71, -2
	s_waitcnt lgkmcnt(0)
	v_mov_b32_e32 v3, v2
	v_mov_b32_e32 v4, v2
	v_mov_b32_e32 v5, v2
	v_mov_b32_e32 v6, v2
	v_mov_b32_e32 v7, v2
	v_mov_b32_e32 v8, v2
	v_mov_b32_e32 v9, v2
	v_mov_b32_e32 v18, v2
	v_mov_b32_e32 v19, v2
	v_mov_b32_e32 v20, v2
	v_mov_b32_e32 v21, v2
	v_mov_b32_e32 v22, v2
	v_mov_b32_e32 v23, v2
	v_mov_b32_e32 v24, v2
	v_mov_b32_e32 v25, v2
	v_mov_b32_e32 v34, v2
	v_mov_b32_e32 v35, v2
	v_mov_b32_e32 v36, v2
	v_mov_b32_e32 v37, v2
	v_mov_b32_e32 v38, v2
	v_mov_b32_e32 v39, v2
	v_mov_b32_e32 v40, v2
	v_mov_b32_e32 v41, v2
	v_mov_b32_e32 v50, v2
	v_mov_b32_e32 v51, v2
	v_mov_b32_e32 v52, v2
	v_mov_b32_e32 v53, v2
	v_mov_b32_e32 v54, v2
	v_mov_b32_e32 v55, v2
	v_mov_b32_e32 v56, v2
	v_mov_b32_e32 v57, v2
	v_mov_b32_e32 v10, v2
	v_mov_b32_e32 v11, v2
	v_mov_b32_e32 v12, v2
	v_mov_b32_e32 v13, v2
	v_mov_b32_e32 v14, v2
	v_mov_b32_e32 v15, v2
	v_mov_b32_e32 v16, v2
	v_mov_b32_e32 v17, v2
	v_mov_b32_e32 v26, v2
	v_mov_b32_e32 v27, v2
	v_mov_b32_e32 v28, v2
	v_mov_b32_e32 v29, v2
	v_mov_b32_e32 v30, v2
	v_mov_b32_e32 v31, v2
	v_mov_b32_e32 v32, v2
	v_mov_b32_e32 v33, v2
	v_mov_b32_e32 v42, v2
	v_mov_b32_e32 v43, v2
	v_mov_b32_e32 v44, v2
	v_mov_b32_e32 v45, v2
	v_mov_b32_e32 v46, v2
	v_mov_b32_e32 v47, v2
	v_mov_b32_e32 v48, v2
	v_mov_b32_e32 v49, v2
	v_mov_b32_e32 v58, v2
	v_mov_b32_e32 v59, v2
	v_mov_b32_e32 v60, v2
	v_mov_b32_e32 v61, v2
	v_mov_b32_e32 v62, v2
	v_mov_b32_e32 v63, v2
	v_mov_b32_e32 v64, v2
	v_mov_b32_e32 v65, v2
	v_mov_b32_e32 v66, v2
	v_mov_b32_e32 v67, v2
	v_mov_b32_e32 v68, v2
	v_mov_b32_e32 v69, v2
	v_mov_b32_e32 v70, v2
	v_mov_b32_e32 v71, v2
	v_mov_b32_e32 v72, v2
	v_mov_b32_e32 v73, v2
	v_mov_b32_e32 v82, v2
	v_mov_b32_e32 v83, v2
	v_mov_b32_e32 v84, v2
	v_mov_b32_e32 v85, v2
	v_mov_b32_e32 v86, v2
	v_mov_b32_e32 v87, v2
	v_mov_b32_e32 v88, v2
	v_mov_b32_e32 v89, v2
	v_mov_b32_e32 v98, v2
	v_mov_b32_e32 v99, v2
	v_mov_b32_e32 v100, v2
	v_mov_b32_e32 v101, v2
	v_mov_b32_e32 v102, v2
	v_mov_b32_e32 v103, v2
	v_mov_b32_e32 v104, v2
	v_mov_b32_e32 v105, v2
	v_mov_b32_e32 v114, v2
	v_mov_b32_e32 v115, v2
	v_mov_b32_e32 v116, v2
	v_mov_b32_e32 v117, v2
	v_mov_b32_e32 v118, v2
	v_mov_b32_e32 v119, v2
	v_mov_b32_e32 v120, v2
	v_mov_b32_e32 v121, v2
	v_mov_b32_e32 v74, v2
	v_mov_b32_e32 v75, v2
	v_mov_b32_e32 v76, v2
	v_mov_b32_e32 v77, v2
	v_mov_b32_e32 v78, v2
	v_mov_b32_e32 v79, v2
	v_mov_b32_e32 v80, v2
	v_mov_b32_e32 v81, v2
	v_mov_b32_e32 v90, v2
	v_mov_b32_e32 v91, v2
	v_mov_b32_e32 v92, v2
	v_mov_b32_e32 v93, v2
	v_mov_b32_e32 v94, v2
	v_mov_b32_e32 v95, v2
	v_mov_b32_e32 v96, v2
	v_mov_b32_e32 v97, v2
	v_mov_b32_e32 v106, v2
	v_mov_b32_e32 v107, v2
	v_mov_b32_e32 v108, v2
	v_mov_b32_e32 v109, v2
	v_mov_b32_e32 v110, v2
	v_mov_b32_e32 v111, v2
	v_mov_b32_e32 v112, v2
	v_mov_b32_e32 v113, v2
	v_mov_b32_e32 v122, v2
	v_mov_b32_e32 v123, v2
	v_mov_b32_e32 v124, v2
	v_mov_b32_e32 v125, v2
	v_mov_b32_e32 v126, v2
	v_mov_b32_e32 v127, v2
	v_mov_b32_e32 v128, v2
	v_mov_b32_e32 v129, v2
	.p2align 3

.LBB0_3003:
	s_ashr_i32 s43, s42, 31
	s_lshl_b64 s[44:45], s[42:43], 20
	s_add_u32 s44, s12, s44
	s_addc_u32 s45, s13, s45
	s_and_b64 s[46:47], s[8:9], exec
	s_cselect_b32 s43, s45, s65
	s_cselect_b32 s59, s44, s64
	s_ashr_i32 s41, s40, 31
	s_lshl_b64 s[46:47], s[40:41], 20
	s_add_u32 s46, s26, s46
	s_addc_u32 s47, s27, s47
	s_and_b64 s[66:67], s[8:9], exec
	s_cselect_b32 s41, s47, s63
	s_cselect_b32 s68, s46, s62
	s_add_u32 s69, s62, 0x100
	s_addc_u32 s70, s63, 0
	s_add_u32 s62, s64, 0x80080
	v_mov_b32_e32 v2, 0
	s_addc_u32 s63, s65, 0
	s_mov_b32 s71, -2
	s_waitcnt lgkmcnt(0)
	v_mov_b32_e32 v3, v2
	v_mov_b32_e32 v4, v2
	v_mov_b32_e32 v5, v2
	v_mov_b32_e32 v6, v2
	v_mov_b32_e32 v7, v2
	v_mov_b32_e32 v8, v2
	v_mov_b32_e32 v9, v2
	v_mov_b32_e32 v18, v2
	v_mov_b32_e32 v19, v2
	v_mov_b32_e32 v20, v2
	v_mov_b32_e32 v21, v2
	v_mov_b32_e32 v22, v2
	v_mov_b32_e32 v23, v2
	v_mov_b32_e32 v24, v2
	v_mov_b32_e32 v25, v2
	v_mov_b32_e32 v34, v2
	v_mov_b32_e32 v35, v2
	v_mov_b32_e32 v36, v2
	v_mov_b32_e32 v37, v2
	v_mov_b32_e32 v38, v2
	v_mov_b32_e32 v39, v2
	v_mov_b32_e32 v40, v2
	v_mov_b32_e32 v41, v2
	v_mov_b32_e32 v50, v2
	v_mov_b32_e32 v51, v2
	v_mov_b32_e32 v52, v2
	v_mov_b32_e32 v53, v2
	v_mov_b32_e32 v54, v2
	v_mov_b32_e32 v55, v2
	v_mov_b32_e32 v56, v2
	v_mov_b32_e32 v57, v2
	v_mov_b32_e32 v10, v2
	v_mov_b32_e32 v11, v2
	v_mov_b32_e32 v12, v2
	v_mov_b32_e32 v13, v2
	v_mov_b32_e32 v14, v2
	v_mov_b32_e32 v15, v2
	v_mov_b32_e32 v16, v2
	v_mov_b32_e32 v17, v2
	v_mov_b32_e32 v26, v2
	v_mov_b32_e32 v27, v2
	v_mov_b32_e32 v28, v2
	v_mov_b32_e32 v29, v2
	v_mov_b32_e32 v30, v2
	v_mov_b32_e32 v31, v2
	v_mov_b32_e32 v32, v2
	v_mov_b32_e32 v33, v2
	v_mov_b32_e32 v42, v2
	v_mov_b32_e32 v43, v2
	v_mov_b32_e32 v44, v2
	v_mov_b32_e32 v45, v2
	v_mov_b32_e32 v46, v2
	v_mov_b32_e32 v47, v2
	v_mov_b32_e32 v48, v2
	v_mov_b32_e32 v49, v2
	v_mov_b32_e32 v58, v2
	v_mov_b32_e32 v59, v2
	v_mov_b32_e32 v60, v2
	v_mov_b32_e32 v61, v2
	v_mov_b32_e32 v62, v2
	v_mov_b32_e32 v63, v2
	v_mov_b32_e32 v64, v2
	v_mov_b32_e32 v65, v2
	v_mov_b32_e32 v66, v2
	v_mov_b32_e32 v67, v2
	v_mov_b32_e32 v68, v2
	v_mov_b32_e32 v69, v2
	v_mov_b32_e32 v70, v2
	v_mov_b32_e32 v71, v2
	v_mov_b32_e32 v72, v2
	v_mov_b32_e32 v73, v2
	v_mov_b32_e32 v82, v2
	v_mov_b32_e32 v83, v2
	v_mov_b32_e32 v84, v2
	v_mov_b32_e32 v85, v2
	v_mov_b32_e32 v86, v2
	v_mov_b32_e32 v87, v2
	v_mov_b32_e32 v88, v2
	v_mov_b32_e32 v89, v2
	v_mov_b32_e32 v98, v2
	v_mov_b32_e32 v99, v2
	v_mov_b32_e32 v100, v2
	v_mov_b32_e32 v101, v2
	v_mov_b32_e32 v102, v2
	v_mov_b32_e32 v103, v2
	v_mov_b32_e32 v104, v2
	v_mov_b32_e32 v105, v2
	v_mov_b32_e32 v114, v2
	v_mov_b32_e32 v115, v2
	v_mov_b32_e32 v116, v2
	v_mov_b32_e32 v117, v2
	v_mov_b32_e32 v118, v2
	v_mov_b32_e32 v119, v2
	v_mov_b32_e32 v120, v2
	v_mov_b32_e32 v121, v2
	v_mov_b32_e32 v74, v2
	v_mov_b32_e32 v75, v2
	v_mov_b32_e32 v76, v2
	v_mov_b32_e32 v77, v2
	v_mov_b32_e32 v78, v2
	v_mov_b32_e32 v79, v2
	v_mov_b32_e32 v80, v2
	v_mov_b32_e32 v81, v2
	v_mov_b32_e32 v90, v2
	v_mov_b32_e32 v91, v2
	v_mov_b32_e32 v92, v2
	v_mov_b32_e32 v93, v2
	v_mov_b32_e32 v94, v2
	v_mov_b32_e32 v95, v2
	v_mov_b32_e32 v96, v2
	v_mov_b32_e32 v97, v2
	v_mov_b32_e32 v106, v2
	v_mov_b32_e32 v107, v2
	v_mov_b32_e32 v108, v2
	v_mov_b32_e32 v109, v2
	v_mov_b32_e32 v110, v2
	v_mov_b32_e32 v111, v2
	v_mov_b32_e32 v112, v2
	v_mov_b32_e32 v113, v2
	v_mov_b32_e32 v122, v2
	v_mov_b32_e32 v123, v2
	v_mov_b32_e32 v124, v2
	v_mov_b32_e32 v125, v2
	v_mov_b32_e32 v126, v2
	v_mov_b32_e32 v127, v2
	v_mov_b32_e32 v128, v2
	v_mov_b32_e32 v129, v2
	.p2align 3
